# stack: adds retkv K-rot prefetch, sb prologue wait relaxation, aligned key tiles
# baseline (speedup 1.0000x reference)
; #define LAS __attribute__((address_space(3)))
; __device__ __forceinline__ float bflo(unsigned u) { return __uint_as_float(u << 16); }
; __device__ __forceinline__ float bfhi(unsigned u) { return __uint_as_float(u & 0xffff0000u); }
; __device__ __forceinline__ float sx(float v, int m, int lane) { return __builtin_bit_cast(float, __builtin_amdgcn_ds_bpermute((lane ^ m) << 2, __builtin_bit_cast(int, v))); }
; __device__ __forceinline__ void sb_item(const bf16_t* hbuf, const float* kmax2, bf16_t* mixed, LAS bf16_t* vT, int item, int lane) {
;     const int bh = item >> 10, qt = item & 1023, b = bh / 6, h = bh % 6, tq0 = qt * 16; const size_t row0 = (size_t)b * SEQ + tq0;
;     const int r = lane & 15, q = lane >> 4;
;     bf16x8 qf[2]; float bound, carry = 0.f;
;     const float km2 = kmax2[bh];
;     { float s = 0.f;
; #pragma unroll
;       for (int ks = 0; ks < 2; ++ks) { const u32x4 v = *(const u32x4*)(hbuf + (row0 + r) * INWP + C_SBQ + h * 64 + 32 * ks + 8 * q); qf[ks] = as_bf16x8(v);
;           s += bflo(v.x) * bflo(v.x) + bfhi(v.x) * bfhi(v.x) + bflo(v.y) * bflo(v.y) + bfhi(v.y) * bfhi(v.y) + bflo(v.z) * bflo(v.z) + bfhi(v.z) * bfhi(v.z) + bflo(v.w) * bflo(v.w) + bfhi(v.w) * bfhi(v.w); }
;       s += sx(s, 16, lane); s += sx(s, 32, lane);
;       bound = sqrtf(s * km2) * 0.125f * 1.01f + 0.05f; }
;     const int qpos = tq0 + r;
;     f32x4 O[4];
; #pragma unroll
;     for (int et = 0; et < 4; ++et) O[et] = (f32x4){0.f, 0.f, 0.f, 0.f};
;     const int cr = lane >> 3, dc = lane & 7;
;     const bf16_t* seqp = hbuf + (size_t)b * SEQ * INWP + h * 64;
;     u32x4 vreg[8], kreg[8];
;     { const int k0 = tq0 + 16 - 64;
; #pragma unroll
;       for (int i = 0; i < 8; ++i) vreg[i] = *(const u32x4*)(seqp + (size_t)max(k0 + cr + 8 * i, 0) * INWP + C_SBV + 8 * dc);
; #pragma unroll
;       for (int i = 0; i < 8; ++i) kreg[i] = *(const u32x4*)(seqp + (size_t)max(k0 + 16 * (i >> 1) + r, 0) * INWP + C_SBK + 32 * (i & 1) + 8 * q); }
.LBB0_234:
	s_and_b32 s98, s12, 3
	s_lshl_b32 s98, s98, 3
	s_bfe_u32 s99, s12, 0x30002
	s_add_i32 s98, s98, s99
	s_and_b32 s99, s12, 0xffffffe0
	s_or_b32 s98, s98, s99
	s_ashr_i32 s0, s98, 10
	s_mul_hi_i32 s1, s0, 0x2aaaaaab
	s_lshr_b32 s17, s1, 31
	s_add_i32 s20, s1, s17
	s_mul_i32 s1, s20, 6
	s_sub_i32 s17, s0, s1
	s_lshl_b32 s1, s98, 4
	s_ashr_i32 s21, s20, 31
	s_and_b32 s26, s1, 0x3ff0
	s_lshl_b64 s[22:23], s[20:21], 14
	s_ashr_i32 s1, s0, 31
	s_or_b32 s21, s22, s26
	s_lshl_b64 s[0:1], s[0:1], 2
	s_add_u32 s0, s75, s0
	s_addc_u32 s1, s74, s1
	v_or_b32_e32 v34, s21, v122
	v_mov_b64_e32 v[8:9], s[42:43]
	s_lshl_b32 s72, s17, 6
	global_load_dword v16, v33, s[0:1] offset:1024
	v_mad_u64_u32 v[8:9], s[0:1], v34, s5, v[8:9]
	s_ashr_i32 s73, s72, 31
	v_mov_b32_e32 v35, s23
	v_mad_i32_i24 v9, s23, v207, v9
	s_lshl_b64 s[22:23], s[72:73], 1
	v_lshl_add_u64 v[8:9], v[8:9], 0, s[22:23]
	v_lshlrev_b32_e32 v32, 1, v124
	v_lshl_add_u64 v[12:13], v[8:9], 0, v[32:33]
	global_load_dwordx4 v[8:11], v[12:13], off offset:512
	global_load_dwordx4 v[212:215], v[12:13], off offset:576
	s_mov_b32 s0, 0xf800000
	v_lshlrev_b32_e32 v88, 1, v126
	v_mov_b32_e32 v89, v33
	v_mov_b32_e32 v153, 0
	v_or_b32_e32 v155, s26, v122
	v_mov_b32_e32 v100, 0
	v_mov_b32_e32 v101, v153
	v_mov_b32_e32 v102, v153
	v_mov_b32_e32 v103, v153
	v_mov_b32_e32 v96, 0
	v_mov_b32_e32 v97, v153
	v_mov_b32_e32 v98, v153
	v_mov_b32_e32 v99, v153
	v_mov_b32_e32 v92, 0
	v_mov_b32_e32 v93, v153
	v_mov_b32_e32 v94, v153
	v_mov_b32_e32 v95, v153
	v_mov_b32_e32 v90, v153
	v_mov_b32_e32 v91, v153
	s_waitcnt vmcnt(0)
	v_and_b32_e32 v15, 0xffff0000, v8
	v_lshlrev_b32_e32 v14, 16, v8
	v_mul_f32_e32 v17, v15, v15
	v_fmac_f32_e32 v17, v14, v14
	v_lshlrev_b32_e32 v14, 16, v9
	v_fmac_f32_e32 v17, v14, v14
	v_and_b32_e32 v14, 0xffff0000, v9
	v_fmac_f32_e32 v17, v14, v14
	v_lshlrev_b32_e32 v14, 16, v10
	v_fmac_f32_e32 v17, v14, v14
	v_and_b32_e32 v14, 0xffff0000, v10
	v_fmac_f32_e32 v17, v14, v14
	v_lshlrev_b32_e32 v14, 16, v11
	v_fmac_f32_e32 v17, v14, v14
	v_and_b32_e32 v14, 0xffff0000, v11
	v_fmac_f32_e32 v17, v14, v14
	v_mov_b32_e32 v12, v212
	v_mov_b32_e32 v13, v213
	v_mov_b32_e32 v14, v214
	v_mov_b32_e32 v15, v215
	v_and_b32_e32 v19, 0xffff0000, v12
	v_lshlrev_b32_e32 v18, 16, v12
	v_mul_f32_e32 v19, v19, v19
	v_fmac_f32_e32 v19, v18, v18
	v_lshlrev_b32_e32 v18, 16, v13
	v_fmac_f32_e32 v19, v18, v18
	v_and_b32_e32 v18, 0xffff0000, v13
	v_fmac_f32_e32 v19, v18, v18
	v_lshlrev_b32_e32 v18, 16, v14
	v_fmac_f32_e32 v19, v18, v18
	v_and_b32_e32 v18, 0xffff0000, v14
	v_fmac_f32_e32 v19, v18, v18
	v_lshlrev_b32_e32 v18, 16, v15
	v_fmac_f32_e32 v19, v18, v18
	v_and_b32_e32 v18, 0xffff0000, v15
	v_fmac_f32_e32 v19, v18, v18
	v_add_f32_e32 v17, v17, v19
	ds_bpermute_b32 v18, v132, v17
	s_waitcnt lgkmcnt(0)
	v_add_f32_e32 v17, v17, v18
	ds_bpermute_b32 v18, v133, v17
	s_waitcnt lgkmcnt(0)
	v_add_f32_e32 v17, v17, v18
	v_mul_f32_e32 v16, v16, v17
	v_cmp_gt_f32_e32 vcc, s0, v16
	v_mul_f32_e32 v17, 0x4f800000, v16
	s_nop 0
	v_cndmask_b32_e32 v16, v16, v17, vcc
	v_sqrt_f32_e32 v17, v16
	s_nop 0
	v_add_u32_e32 v18, -1, v17
	v_fma_f32 v19, -v18, v17, v16
	v_cmp_ge_f32_e64 s[0:1], 0, v19
	v_add_u32_e32 v19, 1, v17
	s_nop 0
	v_cndmask_b32_e64 v18, v17, v18, s[0:1]
	v_fma_f32 v17, -v19, v17, v16
	v_cmp_lt_f32_e64 s[0:1], 0, v17
	s_nop 1
	v_cndmask_b32_e64 v17, v18, v19, s[0:1]
	s_mul_i32 s1, s20, 0x6000000
	s_mul_hi_i32 s0, s20, 0x6000000
	s_add_u32 s1, s42, s1
	v_mul_f32_e32 v18, 0x37800000, v17
	s_addc_u32 s17, s43, s0
	v_cndmask_b32_e32 v17, v17, v18, vcc
	v_cmp_class_f32_e32 vcc, v16, v209
	s_add_u32 s0, s1, s22
	s_addc_u32 s1, s17, s23
	v_cndmask_b32_e32 v16, v17, v16, vcc
	s_and_b32 s17, s26, 0xffffffc0
	v_mul_f32_e32 v16, 0x3e000000, v16
	v_or_b32_e32 v48, s17, v122
	v_or_b32_e32 v86, s17, v134
	v_fmamk_f32 v154, v16, 0x3f8147ae, v170
	v_max_i32_e32 v16, 0xffffffd0, v48
	v_max_i32_e32 v24, 0xffffffe0, v48
	v_max_i32_e32 v40, -16, v48
	v_max_i32_e32 v64, 0xffffffd8, v86
	v_max_i32_e32 v68, 0xffffffe0, v86
	v_add_u32_e32 v16, 48, v16
	v_mov_b64_e32 v[84:85], s[0:1]
	v_add_u32_e32 v24, 32, v24
	v_add_u32_e32 v40, 16, v40
	v_max_i32_e32 v48, 0, v48
	v_add_u32_e32 v64, 40, v64
	v_add_u32_e32 v68, 32, v68
	v_mad_u64_u32 v[16:17], s[20:21], v16, s5, v[84:85]
	v_mad_u64_u32 v[24:25], s[20:21], v24, s5, v[84:85]
	v_mad_u64_u32 v[40:41], s[20:21], v40, s5, v[84:85]
	v_mad_u64_u32 v[48:49], s[20:21], v48, s5, v[84:85]
	v_mad_u64_u32 v[64:65], s[20:21], v64, s5, v[84:85]
	v_mad_u64_u32 v[68:69], s[20:21], v68, s5, v[84:85]
	v_lshl_add_u64 v[20:21], v[16:17], 0, v[32:33]
	v_lshl_add_u64 v[28:29], v[24:25], 0, v[32:33]
	v_lshl_add_u64 v[44:45], v[40:41], 0, v[32:33]
	v_lshl_add_u64 v[52:53], v[48:49], 0, v[32:33]
	v_lshl_add_u64 v[64:65], v[64:65], 0, v[88:89]
	v_lshl_add_u64 v[68:69], v[68:69], 0, v[88:89]
	global_load_dwordx4 v[16:19], v[20:21], off offset:1344
	s_nop 0
	global_load_dwordx4 v[20:23], v[20:21], off offset:1280
	s_nop 0
	global_load_dwordx4 v[24:27], v[28:29], off offset:1344
	s_nop 0
	global_load_dwordx4 v[28:31], v[28:29], off offset:1280
	s_nop 0
	global_load_dwordx4 v[40:43], v[44:45], off offset:1344
	s_nop 0
	global_load_dwordx4 v[44:47], v[44:45], off offset:1280
	s_nop 0
	global_load_dwordx4 v[48:51], v[52:53], off offset:1344
	s_nop 0
	global_load_dwordx4 v[52:55], v[52:53], off offset:1280
	v_max_i32_e32 v76, -16, v86
	global_load_dwordx4 v[64:67], v[64:65], off offset:2048
	v_add_u32_e32 v76, 16, v76
	global_load_dwordx4 v[72:75], v[68:69], off offset:2048
	v_max_i32_e32 v68, 0xffffffe8, v86
	v_add_u32_e32 v68, 24, v68
	v_mad_u64_u32 v[68:69], s[20:21], v68, s5, v[84:85]
	v_mad_u64_u32 v[76:77], s[20:21], v76, s5, v[84:85]
	v_lshl_add_u64 v[68:69], v[68:69], 0, v[88:89]
	v_lshl_add_u64 v[76:77], v[76:77], 0, v[88:89]
	v_max_i32_e32 v56, 0xffffffc8, v86
	v_max_i32_e32 v60, 0xffffffd0, v86
	global_load_dwordx4 v[68:71], v[68:69], off offset:2048
	v_add_u32_e32 v56, 56, v56
	global_load_dwordx4 v[80:83], v[76:77], off offset:2048
	v_or_b32_e32 v76, 8, v86
	v_add_u32_e32 v60, 48, v60
	v_max_i32_e32 v76, 0, v76
	v_max_i32_e32 v86, 0, v86
	v_mad_u64_u32 v[56:57], s[20:21], v56, s5, v[84:85]
	v_mad_u64_u32 v[60:61], s[20:21], v60, s5, v[84:85]
	v_mad_u64_u32 v[76:77], s[20:21], v76, s5, v[84:85]
	v_mad_u64_u32 v[84:85], s[20:21], v86, s5, v[84:85]
	v_lshl_add_u64 v[56:57], v[56:57], 0, v[88:89]
	v_lshl_add_u64 v[60:61], v[60:61], 0, v[88:89]
	v_lshl_add_u64 v[76:77], v[76:77], 0, v[88:89]
	v_lshl_add_u64 v[84:85], v[84:85], 0, v[88:89]
	global_load_dwordx4 v[56:59], v[56:57], off offset:2048
	v_lshl_add_u64 v[128:129], s[0:1], 0, v[88:89]
	global_load_dwordx4 v[60:63], v[60:61], off offset:2048
	v_lshl_add_u64 v[130:131], s[0:1], 0, v[32:33]
	global_load_dwordx4 v[76:79], v[76:77], off offset:2048
	v_mov_b32_e32 v88, 0
	global_load_dwordx4 v[84:87], v[84:85], off offset:2048
	v_mov_b32_e32 v89, v153
	s_branch .LBB0_236

; #define LAS __attribute__((address_space(3)))
; __device__ __forceinline__ float bflo(unsigned u) { return __uint_as_float(u << 16); }
; __device__ __forceinline__ float bfhi(unsigned u) { return __uint_as_float(u & 0xffff0000u); }
; __device__ __forceinline__ float sx(float v, int m, int lane) { return __builtin_bit_cast(float, __builtin_amdgcn_ds_bpermute((lane ^ m) << 2, __builtin_bit_cast(int, v))); }
; __device__ __forceinline__ void sb_item(const bf16_t* hbuf, const float* kmax2, bf16_t* mixed, LAS bf16_t* vT, int item, int lane) {
;     const int bh = item >> 10, qt = item & 1023, b = bh / 6, h = bh % 6, tq0 = qt * 16; const size_t row0 = (size_t)b * SEQ + tq0;
;     const int r = lane & 15, q = lane >> 4;
;     bf16x8 qf[2]; float bound, carry = 0.f;
;     const float km2 = kmax2[bh];
;     { float s = 0.f;
; #pragma unroll
;       for (int ks = 0; ks < 2; ++ks) { const u32x4 v = *(const u32x4*)(hbuf + (row0 + r) * INWP + C_SBQ + h * 64 + 32 * ks + 8 * q); qf[ks] = as_bf16x8(v);
;           s += bflo(v.x) * bflo(v.x) + bfhi(v.x) * bfhi(v.x) + bflo(v.y) * bflo(v.y) + bfhi(v.y) * bfhi(v.y) + bflo(v.z) * bflo(v.z) + bfhi(v.z) * bfhi(v.z) + bflo(v.w) * bflo(v.w) + bfhi(v.w) * bfhi(v.w); }
;       s += sx(s, 16, lane); s += sx(s, 32, lane);
;       bound = sqrtf(s * km2) * 0.125f * 1.01f + 0.05f; }
;     const int qpos = tq0 + r;
;     f32x4 O[4];
; #pragma unroll
;     for (int et = 0; et < 4; ++et) O[et] = (f32x4){0.f, 0.f, 0.f, 0.f};
;     const int cr = lane >> 3, dc = lane & 7;
;     const bf16_t* seqp = hbuf + (size_t)b * SEQ * INWP + h * 64;
;     u32x4 vreg[8], kreg[8];
;     { const int k0 = tq0 + 16 - 64;
; #pragma unroll
;       for (int i = 0; i < 8; ++i) vreg[i] = *(const u32x4*)(seqp + (size_t)max(k0 + cr + 8 * i, 0) * INWP + C_SBV + 8 * dc);
; #pragma unroll
;       for (int i = 0; i < 8; ++i) kreg[i] = *(const u32x4*)(seqp + (size_t)max(k0 + 16 * (i >> 1) + r, 0) * INWP + C_SBK + 32 * (i & 1) + 8 * q); }
.LBB0_283:
	s_ashr_i32 s20, s15, 10
	s_mul_hi_i32 s0, s20, 0x2aaaaaab
	s_lshr_b32 s1, s0, 31
	s_add_i32 s0, s0, s1
	s_mul_i32 s1, s0, 6
	s_sub_i32 s17, s20, s1
	s_lshl_b32 s1, s15, 4
	s_and_b32 s26, s1, 0x3ff0
	s_ashr_i32 s1, s0, 31
	s_lshl_b64 s[22:23], s[0:1], 14
	s_ashr_i32 s21, s20, 31
	s_or_b32 s22, s22, s26
	s_lshl_b64 s[20:21], s[20:21], 2
	s_add_u32 s38, s75, s20
	v_lshl_add_u64 v[124:125], s[22:23], 0, v[122:123]
	v_mov_b64_e32 v[4:5], s[42:43]
	s_addc_u32 s39, s74, s21
	v_mad_u64_u32 v[4:5], s[20:21], v124, s5, v[4:5]
	v_mov_b32_e32 v6, v5
	v_mad_u64_u32 v[6:7], s[20:21], v125, s5, v[6:7]
	s_lshl_b32 s20, s17, 6
	s_ashr_i32 s21, s20, 31
	v_mov_b32_e32 v5, v6
	s_lshl_b64 s[22:23], s[20:21], 1
	v_lshl_add_u64 v[4:5], v[4:5], 0, s[22:23]
	s_waitcnt vmcnt(0)
	v_lshl_add_u64 v[8:9], v[4:5], 0, v[116:117]
	global_load_dwordx4 v[4:7], v[8:9], off offset:512
	global_load_dword v54, v33, s[38:39] offset:1024
	s_mul_hi_i32 s1, s0, 0x6000000
	global_load_dwordx4 v[8:11], v[8:9], off offset:576
	s_mul_i32 s0, s0, 0x6000000
	s_add_u32 s0, s42, s0
	s_addc_u32 s1, s43, s1
	s_add_u32 s22, s0, s22
	s_addc_u32 s23, s1, s23
	s_and_b32 s17, s26, 0xffffffc0
	v_or_b32_e32 v12, s17, v130
	v_or_b32_e32 v55, s17, v134
	v_mov_b64_e32 v[48:49], s[22:23]
	v_max_i32_e32 v13, 0xffffffd0, v12
	v_max_i32_e32 v14, 0xffffffe0, v12
	v_max_i32_e32 v15, -16, v12
	v_max_i32_e32 v12, 0, v12
	v_max_i32_e32 v16, 0xffffffc8, v55
	v_max_i32_e32 v17, 0xffffffd0, v55
	v_max_i32_e32 v18, 0xffffffd8, v55
	v_max_i32_e32 v19, 0xffffffe0, v55
	v_add_u32_e32 v20, 48, v13
	v_add_u32_e32 v21, 32, v14
	v_add_u32_e32 v22, 16, v15
	v_mad_u64_u32 v[12:13], s[0:1], v12, s5, v[48:49]
	v_add_u32_e32 v23, 56, v16
	v_add_u32_e32 v24, 48, v17
	v_add_u32_e32 v26, 40, v18
	v_add_u32_e32 v28, 32, v19
	v_mad_u64_u32 v[14:15], s[0:1], v20, s5, v[48:49]
	v_mad_u64_u32 v[16:17], s[0:1], v21, s5, v[48:49]
	v_mad_u64_u32 v[18:19], s[0:1], v22, s5, v[48:49]
	v_lshl_add_u64 v[20:21], v[12:13], 0, v[116:117]
	v_mad_u64_u32 v[22:23], s[0:1], v23, s5, v[48:49]
	v_mad_u64_u32 v[24:25], s[0:1], v24, s5, v[48:49]
	v_mad_u64_u32 v[26:27], s[0:1], v26, s5, v[48:49]
	v_mad_u64_u32 v[28:29], s[0:1], v28, s5, v[48:49]
	v_lshl_add_u64 v[30:31], v[14:15], 0, v[116:117]
	v_lshl_add_u64 v[40:41], v[16:17], 0, v[116:117]
	v_lshl_add_u64 v[42:43], v[18:19], 0, v[116:117]
	global_load_dwordx4 v[12:15], v[20:21], off offset:1344
	global_load_dwordx4 v[16:19], v[20:21], off offset:1280
	v_lshl_add_u64 v[20:21], v[22:23], 0, v[118:119]
	v_lshl_add_u64 v[22:23], v[24:25], 0, v[118:119]
	v_lshl_add_u64 v[44:45], v[26:27], 0, v[118:119]
	v_lshl_add_u64 v[50:51], v[28:29], 0, v[118:119]
	global_load_dwordx4 v[68:71], v[30:31], off offset:1344
	global_load_dwordx4 v[72:75], v[30:31], off offset:1280
	global_load_dwordx4 v[56:59], v[40:41], off offset:1344
	global_load_dwordx4 v[60:63], v[40:41], off offset:1280
	s_nop 0
	global_load_dwordx4 v[28:31], v[42:43], off offset:1344
	s_nop 0
	global_load_dwordx4 v[40:43], v[42:43], off offset:1280
	s_nop 0
	global_load_dwordx4 v[24:27], v[20:21], off offset:2048
	s_nop 0
	global_load_dwordx4 v[20:23], v[22:23], off offset:2048
	v_mov_b32_e32 v142, 0
	v_or_b32_e32 v144, s26, v130
	v_lshl_add_u64 v[126:127], s[22:23], 0, v[118:119]
	v_lshl_add_u64 v[128:129], s[22:23], 0, v[116:117]
	v_mov_b32_e32 v76, 0
	v_mov_b32_e32 v77, v142
	v_mov_b32_e32 v78, v142
	v_mov_b32_e32 v79, v142
	v_mov_b32_e32 v65, v142
	v_mov_b32_e32 v66, v142
	v_mov_b32_e32 v67, v142
	s_waitcnt vmcnt(10)
	v_and_b32_e32 v47, 0xffff0000, v4
	v_lshlrev_b32_e32 v46, 16, v4
	v_mul_f32_e32 v64, v47, v47
	v_lshlrev_b32_e32 v52, 16, v5
	v_fmac_f32_e32 v64, v46, v46
	global_load_dwordx4 v[44:47], v[44:45], off offset:2048
	s_nop 0
	global_load_dwordx4 v[80:83], v[50:51], off offset:2048
	v_max_i32_e32 v50, 0xffffffe8, v55
	v_fmac_f32_e32 v64, v52, v52
	v_add_u32_e32 v50, 24, v50
	v_max_i32_e32 v52, -16, v55
	v_and_b32_e32 v53, 0xffff0000, v5
	v_mad_u64_u32 v[50:51], s[0:1], v50, s5, v[48:49]
	v_add_u32_e32 v52, 16, v52
	v_fmac_f32_e32 v64, v53, v53
	v_lshl_add_u64 v[50:51], v[50:51], 0, v[118:119]
	v_mad_u64_u32 v[52:53], s[0:1], v52, s5, v[48:49]
	v_lshl_add_u64 v[52:53], v[52:53], 0, v[118:119]
	global_load_dwordx4 v[88:91], v[50:51], off offset:2048
	global_load_dwordx4 v[84:87], v[52:53], off offset:2048
	v_or_b32_e32 v50, 8, v55
	v_max_i32_e32 v50, 0, v50
	v_mad_u64_u32 v[50:51], s[0:1], v50, s5, v[48:49]
	v_max_i32_e32 v52, 0, v55
	v_lshl_add_u64 v[50:51], v[50:51], 0, v[118:119]
	v_mad_u64_u32 v[48:49], s[0:1], v52, s5, v[48:49]
	v_lshl_add_u64 v[48:49], v[48:49], 0, v[118:119]
	global_load_dwordx4 v[92:95], v[50:51], off offset:2048
	global_load_dwordx4 v[96:99], v[48:49], off offset:2048
	v_lshlrev_b32_e32 v48, 16, v6
	v_fmac_f32_e32 v64, v48, v48
	v_and_b32_e32 v48, 0xffff0000, v6
	v_fmac_f32_e32 v64, v48, v48
	v_lshlrev_b32_e32 v48, 16, v7
	v_fmac_f32_e32 v64, v48, v48
	v_and_b32_e32 v48, 0xffff0000, v7
	v_and_b32_e32 v49, 0xffff0000, v8
	v_fmac_f32_e32 v64, v48, v48
	v_lshlrev_b32_e32 v48, 16, v8
	v_mul_f32_e32 v49, v49, v49
	v_fmac_f32_e32 v49, v48, v48
	v_lshlrev_b32_e32 v48, 16, v9
	v_fmac_f32_e32 v49, v48, v48
	v_and_b32_e32 v48, 0xffff0000, v9
	v_fmac_f32_e32 v49, v48, v48
	v_lshlrev_b32_e32 v48, 16, v10
	v_fmac_f32_e32 v49, v48, v48
	v_and_b32_e32 v48, 0xffff0000, v10
	v_fmac_f32_e32 v49, v48, v48
	v_lshlrev_b32_e32 v48, 16, v11
	v_fmac_f32_e32 v49, v48, v48
	v_and_b32_e32 v48, 0xffff0000, v11
	v_fmac_f32_e32 v49, v48, v48
	v_add_f32_e32 v48, v64, v49
	ds_bpermute_b32 v49, v132, v48
	s_mov_b32 s0, 0xf800000
	v_mov_b32_e32 v64, 0
	v_mov_b32_e32 v52, 0
	v_mov_b32_e32 v53, v142
	s_waitcnt lgkmcnt(0)
	v_add_f32_e32 v48, v48, v49
	ds_bpermute_b32 v49, v133, v48
	v_mov_b32_e32 v55, v142
	s_waitcnt lgkmcnt(0)
	v_add_f32_e32 v48, v48, v49
	v_mul_f32_e32 v48, v54, v48
	v_mul_f32_e32 v49, 0x4f800000, v48
	v_cmp_gt_f32_e32 vcc, s0, v48
	v_mov_b32_e32 v54, v142
	s_nop 0
	v_cndmask_b32_e32 v48, v48, v49, vcc
	v_sqrt_f32_e32 v49, v48
	s_nop 0
	v_add_u32_e32 v50, -1, v49
	v_fma_f32 v51, -v50, v49, v48
	v_cmp_ge_f32_e64 s[0:1], 0, v51
	v_add_u32_e32 v51, 1, v49
	s_nop 0
	v_cndmask_b32_e64 v50, v49, v50, s[0:1]
	v_fma_f32 v49, -v51, v49, v48
	v_cmp_lt_f32_e64 s[0:1], 0, v49
	s_nop 1
	v_cndmask_b32_e64 v49, v50, v51, s[0:1]
	v_mul_f32_e32 v50, 0x37800000, v49
	v_cndmask_b32_e32 v49, v49, v50, vcc
	v_cmp_class_f32_e32 vcc, v48, v209
	v_mov_b32_e32 v50, v142
	v_mov_b32_e32 v51, v142
	v_cndmask_b32_e32 v48, v49, v48, vcc
	v_mul_f32_e32 v48, 0x3e000000, v48
	v_fmamk_f32 v143, v48, 0x3f8147ae, v170
	v_mov_b32_e32 v48, 0
	v_mov_b32_e32 v49, v142
	s_branch .LBB0_285

; #define LAS __attribute__((address_space(3)))
; __device__ __forceinline__ unsigned pk2(float lo, float hi) { unsigned r; asm("v_cvt_pk_bf16_f32 %0, %1, %2" : "=v"(r) : "v"(lo), "v"(hi)); return r; }
; __device__ __forceinline__ float bflo(unsigned u) { return __uint_as_float(u << 16); }
; __device__ __forceinline__ float bfhi(unsigned u) { return __uint_as_float(u & 0xffff0000u); }
; __device__ __forceinline__ float log2_gamma(int h) { return log2f(1.0f - exp2f(-5.0f - (float)h)); }
; template <bool SCALE>
; __device__ __forceinline__ void load_tile_T(const bf16_t* src, LAS bf16_t* T, int lane, float sc0, float scmul) {
;     const int cr = lane >> 3, dc = lane & 7;
;     u32x4 v[8];
; #pragma unroll
;     for (int i = 0; i < 8; ++i) v[i] = *(const u32x4*)(src + (size_t)(cr + 8 * i) * INWP + 8 * dc);
; #pragma unroll
;     for (int i = 0; i < 8; ++i) { const int row = cr + 8 * i; u32x4 w = v[i];
;         if (SCALE) { const float s = sc0 * __builtin_amdgcn_exp2f(scmul * (float)row);
;             w.x = pk2(bflo(w.x) * s, bfhi(w.x) * s); w.y = pk2(bflo(w.y) * s, bfhi(w.y) * s); w.z = pk2(bflo(w.z) * s, bfhi(w.z) * s); w.w = pk2(bflo(w.w) * s, bfhi(w.w) * s); }
;         LAS bf16_t* t = T + (8 * dc) * TLD + row;
;         t[0 * TLD] = (bf16_t)(w.x & 0xffff); t[1 * TLD] = (bf16_t)(w.x >> 16); t[2 * TLD] = (bf16_t)(w.y & 0xffff); t[3 * TLD] = (bf16_t)(w.y >> 16);
;         t[4 * TLD] = (bf16_t)(w.z & 0xffff); t[5 * TLD] = (bf16_t)(w.z >> 16); t[6 * TLD] = (bf16_t)(w.w & 0xffff); t[7 * TLD] = (bf16_t)(w.w >> 16); }
; }
; __device__ __forceinline__ void retkv_item(const bf16_t* hbuf, const float* rot, float* kvbuf, LAS bf16_t* wl, int item, int lane) {
;     const int bh = item / NCHUNK, n = item % NCHUNK, b = bh / 6, h = bh % 6; const size_t t0 = (size_t)b * SEQ + (size_t)n * 64;
;     LAS bf16_t* kT = wl; LAS bf16_t* vT = wl + 64 * TLD;
;     const float l2g = log2_gamma(h);
;     load_tile_T<true>(hbuf + t0 * INWP + C_RV + h * 64, vT, lane, exp2f(l2g * 63.f), -l2g);
.LBB0_341:
	s_ashr_i32 s37, s36, 31
	s_lshr_b32 s0, s37, 24
	s_add_i32 s0, s36, s0
	s_mul_hi_i32 s1, s36, 0x2aaaaaab
	s_ashr_i32 s15, s0, 8
	s_lshr_b32 s17, s1, 31
	s_ashr_i32 s1, s1, 8
	s_add_i32 s20, s1, s17
	s_mul_hi_i32 s1, s15, 0x2aaaaaab
	s_lshr_b32 s17, s1, 31
	s_add_i32 s1, s1, s17
	s_mul_i32 s1, s1, 6
	s_sub_i32 s26, s15, s1
	s_and_b32 s0, s0, 0xffffff00
	v_cvt_f32_i32_e32 v0, s26
	s_sub_i32 s0, s36, s0
	s_ashr_i32 s21, s20, 31
	s_ashr_i32 s1, s0, 31
	s_lshl_b64 s[20:21], s[20:21], 14
	s_lshl_b64 s[0:1], s[0:1], 6
	s_add_u32 s20, s20, s0
	v_sub_f32_e32 v0, 0xc0a00000, v0
	s_addc_u32 s17, s21, s1
	v_cmp_gt_f32_e64 s[0:1], s47, v0
	v_mov_b32_e32 v51, v33
	v_mov_b32_e32 v53, v33
	v_cndmask_b32_e64 v1, 0, v229, s[0:1]
	v_add_f32_e32 v0, v0, v1
	v_exp_f32_e32 v0, v0
	s_and_b64 s[0:1], s[0:1], exec
	s_cselect_b32 s0, 0xffffffc0, 0
	v_mov_b32_e32 v55, v33
	v_ldexp_f32 v0, v0, s0
	v_sub_f32_e32 v0, 1.0, v0
	v_cmp_gt_f32_e64 s[0:1], s33, v0
	s_and_b64 s[22:23], s[0:1], exec
	s_cselect_b32 s21, 32, 0
	v_ldexp_f32 v0, v0, s21
	v_log_f32_e32 v0, v0
	v_cndmask_b32_e64 v1, 0, v246, s[0:1]
	s_mul_i32 s0, s17, 0x1800
	s_mul_hi_u32 s1, s20, 0x1800
	s_add_i32 s1, s1, s0
	s_mul_i32 s0, s20, 0x1800
	s_add_u32 s21, s42, s0
	v_sub_f32_e32 v61, v0, v1
	s_addc_u32 s23, s43, s1
	s_lshl_b32 s0, s26, 6
	s_ashr_i32 s1, s0, 31
	v_mul_f32_e32 v0, 0x427c0000, v61
	s_lshl_b64 s[38:39], s[0:1], 1
	v_cmp_gt_f32_e64 s[0:1], s47, v0
	s_add_u32 s22, s21, s38
	s_addc_u32 s23, s23, s39
	v_cndmask_b32_e64 v0, 0, v229, s[0:1]
	v_fmac_f32_e32 v0, 0x427c0000, v61
	v_exp_f32_e32 v0, v0
	s_and_b64 s[0:1], s[0:1], exec
	s_cselect_b32 s0, 0xffffffc0, 0
	v_mov_b32_e32 v57, v33
	v_ldexp_f32 v74, v0, s0
	v_lshl_add_u64 v[0:1], s[22:23], 0, v[32:33]
	s_mov_b64 s[0:1], 0x1100
	v_lshl_add_u64 v[70:71], v[0:1], 0, s[0:1]
	v_lshl_add_u64 v[12:13], v[70:71], 0, v[50:51]
	global_load_dwordx4 v[0:3], v[12:13], off
	v_add_co_u32_e64 v4, s[0:1], s41, v12
	v_lshl_add_u64 v[16:17], v[70:71], 0, v[52:53]
	s_nop 0
	v_addc_co_u32_e64 v5, s[0:1], 0, v13, s[0:1]
	global_load_dwordx4 v[4:7], v[4:5], off
	v_add_co_u32_e64 v8, s[0:1], s40, v12
	global_load_dwordx4 v[16:19], v[16:17], off
	s_nop 0
	v_addc_co_u32_e64 v9, s[0:1], 0, v13, s[0:1]
	global_load_dwordx4 v[8:11], v[8:9], off
	v_add_co_u32_e64 v12, s[0:1], s44, v12
	v_lshl_add_u64 v[20:21], v[70:71], 0, v[54:55]
	s_nop 0
	v_addc_co_u32_e64 v13, s[0:1], 0, v13, s[0:1]
	global_load_dwordx4 v[12:15], v[12:13], off
	v_mul_f32_e64 v51, v25, -v61
	global_load_dwordx4 v[20:23], v[20:21], off
	v_exp_f32_e32 v51, v51
	v_lshl_add_u64 v[66:67], v[70:71], 0, v[56:57]
	global_load_dwordx4 v[66:69], v[66:67], off
	v_mov_b32_e32 v59, v33
	v_mul_f32_e32 v51, v74, v51
	v_lshl_add_u64 v[70:71], v[70:71], 0, v[58:59]
	global_load_dwordx4 v[70:73], v[70:71], off
	s_waitcnt vmcnt(7)
	v_lshlrev_b32_e32 v53, 16, v0
	v_and_b32_e32 v0, 0xffff0000, v0
	v_mul_f32_e32 v53, v51, v53
	v_mul_f32_e32 v0, v51, v0
	v_cvt_pk_bf16_f32 v0, v53, v0
	v_lshlrev_b32_e32 v53, 16, v1
	v_and_b32_e32 v1, 0xffff0000, v1
	v_mul_f32_e32 v53, v51, v53
	v_mul_f32_e32 v1, v51, v1
	v_cvt_pk_bf16_f32 v1, v53, v1
	v_lshlrev_b32_e32 v53, 16, v2
	v_and_b32_e32 v2, 0xffff0000, v2
	v_mul_f32_e32 v53, v51, v53
	v_mul_f32_e32 v2, v51, v2
	v_cvt_pk_bf16_f32 v2, v53, v2
	v_lshlrev_b32_e32 v53, 16, v3
	v_and_b32_e32 v3, 0xffff0000, v3
	v_mul_f32_e32 v3, v51, v3
	v_mul_f32_e32 v53, v51, v53
	v_cvt_pk_bf16_f32 v3, v53, v3
	ds_write_b16 v29, v0 offset:9216
	ds_write_b16_d16_hi v29, v0 offset:9360
	ds_write_b16 v29, v1 offset:9504
	ds_write_b16_d16_hi v29, v1 offset:9648
	ds_write_b16 v29, v2 offset:9792
	ds_write_b16_d16_hi v29, v2 offset:9936
	ds_write_b16 v29, v3 offset:10080
	ds_write_b16_d16_hi v29, v3 offset:10224
	v_mul_f32_e64 v0, v31, -v61
	v_exp_f32_e32 v0, v0
	s_waitcnt vmcnt(6)
	v_lshlrev_b32_e32 v1, 16, v4
	v_and_b32_e32 v2, 0xffff0000, v4
	v_and_b32_e32 v3, 0xffff0000, v5
	v_mul_f32_e32 v0, v74, v0
	v_mul_f32_e32 v1, v0, v1
	v_mul_f32_e32 v2, v0, v2
	v_cvt_pk_bf16_f32 v1, v1, v2
	v_lshlrev_b32_e32 v2, 16, v5
	v_mul_f32_e32 v2, v0, v2
	v_mul_f32_e32 v3, v0, v3
	v_cvt_pk_bf16_f32 v2, v2, v3
	v_lshlrev_b32_e32 v3, 16, v6
	v_and_b32_e32 v4, 0xffff0000, v6
	v_mul_f32_e32 v3, v0, v3
	v_mul_f32_e32 v4, v0, v4
	v_cvt_pk_bf16_f32 v3, v3, v4
	v_lshlrev_b32_e32 v4, 16, v7
	v_and_b32_e32 v5, 0xffff0000, v7
	v_mul_f32_e32 v4, v0, v4
	v_mul_f32_e32 v0, v0, v5
	v_cvt_pk_bf16_f32 v0, v4, v0
	ds_write_b16 v29, v1 offset:9232
	ds_write_b16_d16_hi v29, v1 offset:9376
	ds_write_b16 v29, v2 offset:9520
	ds_write_b16_d16_hi v29, v2 offset:9664
	ds_write_b16 v29, v3 offset:9808
	ds_write_b16_d16_hi v29, v3 offset:9952
	ds_write_b16 v29, v0 offset:10096
	ds_write_b16_d16_hi v29, v0 offset:10240
	v_mul_f32_e64 v0, v35, -v61
	v_exp_f32_e32 v0, v0
	s_waitcnt vmcnt(4)
	v_lshlrev_b32_e32 v1, 16, v8
	v_and_b32_e32 v2, 0xffff0000, v8
	v_and_b32_e32 v3, 0xffff0000, v9
	v_mul_f32_e32 v0, v74, v0
	v_mul_f32_e32 v1, v0, v1
	v_mul_f32_e32 v2, v0, v2
	v_cvt_pk_bf16_f32 v1, v1, v2
	v_lshlrev_b32_e32 v2, 16, v9
	v_mul_f32_e32 v2, v0, v2
	v_mul_f32_e32 v3, v0, v3
	v_cvt_pk_bf16_f32 v2, v2, v3
	v_lshlrev_b32_e32 v3, 16, v10
	v_and_b32_e32 v4, 0xffff0000, v10
	v_mul_f32_e32 v3, v0, v3
	v_mul_f32_e32 v4, v0, v4
	v_cvt_pk_bf16_f32 v3, v3, v4
	v_lshlrev_b32_e32 v4, 16, v11
	v_and_b32_e32 v5, 0xffff0000, v11
	v_mul_f32_e32 v4, v0, v4
	v_mul_f32_e32 v0, v0, v5
	v_cvt_pk_bf16_f32 v0, v4, v0
	ds_write_b16 v29, v1 offset:9248
	ds_write_b16_d16_hi v29, v1 offset:9392
	ds_write_b16 v29, v2 offset:9536
	ds_write_b16_d16_hi v29, v2 offset:9680
	ds_write_b16 v29, v3 offset:9824
	ds_write_b16_d16_hi v29, v3 offset:9968
	ds_write_b16 v29, v0 offset:10112
	ds_write_b16_d16_hi v29, v0 offset:10256
	v_mul_f32_e64 v0, v37, -v61
	v_exp_f32_e32 v0, v0
	s_waitcnt vmcnt(3)
; #define LAS __attribute__((address_space(3)))
; __device__ __forceinline__ unsigned pk2(float lo, float hi) { unsigned r; asm("v_cvt_pk_bf16_f32 %0, %1, %2" : "=v"(r) : "v"(lo), "v"(hi)); return r; }
; __device__ __forceinline__ float bflo(unsigned u) { return __uint_as_float(u << 16); }
; __device__ __forceinline__ float bfhi(unsigned u) { return __uint_as_float(u & 0xffff0000u); }
; template <bool SCALE>
; __device__ __forceinline__ void load_tile_T(const bf16_t* src, LAS bf16_t* T, int lane, float sc0, float scmul) {
;     const int cr = lane >> 3, dc = lane & 7;
;     u32x4 v[8];
; #pragma unroll
;     for (int i = 0; i < 8; ++i) v[i] = *(const u32x4*)(src + (size_t)(cr + 8 * i) * INWP + 8 * dc);
; #pragma unroll
;     for (int i = 0; i < 8; ++i) { const int row = cr + 8 * i; u32x4 w = v[i];
;         if (SCALE) { const float s = sc0 * __builtin_amdgcn_exp2f(scmul * (float)row);
;             w.x = pk2(bflo(w.x) * s, bfhi(w.x) * s); w.y = pk2(bflo(w.y) * s, bfhi(w.y) * s); w.z = pk2(bflo(w.z) * s, bfhi(w.z) * s); w.w = pk2(bflo(w.w) * s, bfhi(w.w) * s); }
;         LAS bf16_t* t = T + (8 * dc) * TLD + row;
;         t[0 * TLD] = (bf16_t)(w.x & 0xffff); t[1 * TLD] = (bf16_t)(w.x >> 16); t[2 * TLD] = (bf16_t)(w.y & 0xffff); t[3 * TLD] = (bf16_t)(w.y >> 16);
;         t[4 * TLD] = (bf16_t)(w.z & 0xffff); t[5 * TLD] = (bf16_t)(w.z >> 16); t[6 * TLD] = (bf16_t)(w.w & 0xffff); t[7 * TLD] = (bf16_t)(w.w >> 16); }
; }
; __device__ __forceinline__ void retkv_item(const bf16_t* hbuf, const float* rot, float* kvbuf, LAS bf16_t* wl, int item, int lane) {
;     ...
;     { const int cr = lane >> 3, dc = lane & 7, fc = dc & 3;
; #pragma unroll
;       for (int i = 0; i < 8; ++i) { const int row = cr + 8 * i; const bf16_t* kp = hbuf + (t0 + row) * INWP + C_RK + h * 64;
;           const u32x4 x1 = *(const u32x4*)(kp + 8 * fc), x2 = *(const u32x4*)(kp + 32 + 8 * fc);
;           const int pos = n * 64 + row; u32x4 o1, o2;
;           rot8(x1, x2, rot + (size_t)pos * 32 + 8 * fc, rot + 16384 * 32 + (size_t)pos * 32 + 8 * fc, 0.125f, o1, o2);
	v_lshlrev_b32_e32 v1, 16, v12
	v_and_b32_e32 v2, 0xffff0000, v12
	v_and_b32_e32 v3, 0xffff0000, v13
	v_mul_f32_e32 v0, v74, v0
	v_mul_f32_e32 v1, v0, v1
	v_mul_f32_e32 v2, v0, v2
	v_cvt_pk_bf16_f32 v1, v1, v2
	v_lshlrev_b32_e32 v2, 16, v13
	v_mul_f32_e32 v2, v0, v2
	v_mul_f32_e32 v3, v0, v3
	v_cvt_pk_bf16_f32 v2, v2, v3
	v_lshlrev_b32_e32 v3, 16, v14
	v_and_b32_e32 v4, 0xffff0000, v14
	v_mul_f32_e32 v3, v0, v3
	v_mul_f32_e32 v4, v0, v4
	v_cvt_pk_bf16_f32 v3, v3, v4
	v_lshlrev_b32_e32 v4, 16, v15
	v_and_b32_e32 v5, 0xffff0000, v15
	v_mul_f32_e32 v4, v0, v4
	v_mul_f32_e32 v0, v0, v5
	v_cvt_pk_bf16_f32 v0, v4, v0
	ds_write_b16 v29, v1 offset:9264
	ds_write_b16_d16_hi v29, v1 offset:9408
	ds_write_b16 v29, v2 offset:9552
	ds_write_b16_d16_hi v29, v2 offset:9696
	ds_write_b16 v29, v3 offset:9840
	ds_write_b16_d16_hi v29, v3 offset:9984
	ds_write_b16 v29, v0 offset:10128
	ds_write_b16_d16_hi v29, v0 offset:10272
	v_mul_f32_e64 v0, v39, -v61
	v_exp_f32_e32 v0, v0
	v_lshlrev_b32_e32 v1, 16, v16
	v_and_b32_e32 v2, 0xffff0000, v16
	v_and_b32_e32 v3, 0xffff0000, v17
	v_mul_f32_e32 v0, v74, v0
	v_mul_f32_e32 v1, v0, v1
	v_mul_f32_e32 v2, v0, v2
	v_cvt_pk_bf16_f32 v1, v1, v2
	v_lshlrev_b32_e32 v2, 16, v17
	v_mul_f32_e32 v2, v0, v2
	v_mul_f32_e32 v3, v0, v3
	v_cvt_pk_bf16_f32 v2, v2, v3
	v_lshlrev_b32_e32 v3, 16, v18
	v_and_b32_e32 v4, 0xffff0000, v18
	v_mul_f32_e32 v3, v0, v3
	v_mul_f32_e32 v4, v0, v4
	v_cvt_pk_bf16_f32 v3, v3, v4
	v_lshlrev_b32_e32 v4, 16, v19
	v_and_b32_e32 v5, 0xffff0000, v19
	v_mul_f32_e32 v4, v0, v4
	v_mul_f32_e32 v0, v0, v5
	v_cvt_pk_bf16_f32 v0, v4, v0
	ds_write_b16 v29, v1 offset:9280
	ds_write_b16_d16_hi v29, v1 offset:9424
	ds_write_b16 v29, v2 offset:9568
	ds_write_b16_d16_hi v29, v2 offset:9712
	ds_write_b16 v29, v3 offset:9856
	ds_write_b16_d16_hi v29, v3 offset:10000
	ds_write_b16 v29, v0 offset:10144
	ds_write_b16_d16_hi v29, v0 offset:10288
	v_mul_f32_e64 v0, v41, -v61
	v_exp_f32_e32 v0, v0
	s_waitcnt vmcnt(2)
	v_lshlrev_b32_e32 v1, 16, v20
	v_and_b32_e32 v2, 0xffff0000, v20
	v_and_b32_e32 v3, 0xffff0000, v21
	v_mul_f32_e32 v0, v74, v0
	v_mul_f32_e32 v1, v0, v1
	v_mul_f32_e32 v2, v0, v2
	v_cvt_pk_bf16_f32 v1, v1, v2
	v_lshlrev_b32_e32 v2, 16, v21
	v_mul_f32_e32 v2, v0, v2
	v_mul_f32_e32 v3, v0, v3
	v_cvt_pk_bf16_f32 v2, v2, v3
	v_lshlrev_b32_e32 v3, 16, v22
	v_and_b32_e32 v4, 0xffff0000, v22
	v_mul_f32_e32 v3, v0, v3
	v_mul_f32_e32 v4, v0, v4
	v_cvt_pk_bf16_f32 v3, v3, v4
	v_lshlrev_b32_e32 v4, 16, v23
	v_and_b32_e32 v5, 0xffff0000, v23
	v_mul_f32_e32 v4, v0, v4
	v_mul_f32_e32 v0, v0, v5
	v_cvt_pk_bf16_f32 v0, v4, v0
	ds_write_b16 v29, v1 offset:9296
	ds_write_b16_d16_hi v29, v1 offset:9440
	ds_write_b16 v29, v2 offset:9584
	ds_write_b16_d16_hi v29, v2 offset:9728
	ds_write_b16 v29, v3 offset:9872
	ds_write_b16_d16_hi v29, v3 offset:10016
	ds_write_b16 v29, v0 offset:10160
	ds_write_b16_d16_hi v29, v0 offset:10304
	v_mul_f32_e64 v0, v43, -v61
	v_exp_f32_e32 v0, v0
	s_waitcnt vmcnt(1)
	v_lshlrev_b32_e32 v1, 16, v66
	v_and_b32_e32 v2, 0xffff0000, v66
	v_and_b32_e32 v3, 0xffff0000, v67
	v_mul_f32_e32 v0, v74, v0
	v_mul_f32_e32 v1, v0, v1
	v_mul_f32_e32 v2, v0, v2
	v_cvt_pk_bf16_f32 v1, v1, v2
	v_lshlrev_b32_e32 v2, 16, v67
	v_mul_f32_e32 v2, v0, v2
	v_mul_f32_e32 v3, v0, v3
	v_cvt_pk_bf16_f32 v2, v2, v3
	v_lshlrev_b32_e32 v3, 16, v68
	v_and_b32_e32 v4, 0xffff0000, v68
	v_mul_f32_e32 v3, v0, v3
	v_mul_f32_e32 v4, v0, v4
	v_cvt_pk_bf16_f32 v3, v3, v4
	v_lshlrev_b32_e32 v4, 16, v69
	v_and_b32_e32 v5, 0xffff0000, v69
	v_mul_f32_e32 v4, v0, v4
	v_mul_f32_e32 v0, v0, v5
	v_cvt_pk_bf16_f32 v0, v4, v0
	ds_write_b16 v29, v1 offset:9312
	ds_write_b16_d16_hi v29, v1 offset:9456
	ds_write_b16 v29, v2 offset:9600
	ds_write_b16_d16_hi v29, v2 offset:9744
	ds_write_b16 v29, v3 offset:9888
	ds_write_b16_d16_hi v29, v3 offset:10032
	ds_write_b16 v29, v0 offset:10176
	ds_write_b16_d16_hi v29, v0 offset:10320
	v_mul_f32_e64 v0, v62, -v61
	v_exp_f32_e32 v0, v0
	s_waitcnt vmcnt(0)
	v_lshlrev_b32_e32 v1, 16, v70
	v_and_b32_e32 v2, 0xffff0000, v70
	v_and_b32_e32 v3, 0xffff0000, v71
	v_mul_f32_e32 v0, v74, v0
	v_mul_f32_e32 v1, v0, v1
	v_mul_f32_e32 v2, v0, v2
	v_cvt_pk_bf16_f32 v1, v1, v2
	v_lshlrev_b32_e32 v2, 16, v71
	v_mul_f32_e32 v2, v0, v2
	v_mul_f32_e32 v3, v0, v3
	v_cvt_pk_bf16_f32 v2, v2, v3
	v_lshlrev_b32_e32 v3, 16, v72
	v_and_b32_e32 v4, 0xffff0000, v72
	v_mul_f32_e32 v3, v0, v3
	v_mul_f32_e32 v4, v0, v4
	v_cvt_pk_bf16_f32 v3, v3, v4
	v_lshlrev_b32_e32 v4, 16, v73
	v_and_b32_e32 v5, 0xffff0000, v73
	v_mul_f32_e32 v4, v0, v4
	v_mul_f32_e32 v0, v0, v5
	v_cvt_pk_bf16_f32 v0, v4, v0
	ds_write_b16 v29, v1 offset:9328
	ds_write_b16_d16_hi v29, v1 offset:9472
	ds_write_b16 v29, v2 offset:9616
	ds_write_b16_d16_hi v29, v2 offset:9760
	ds_write_b16 v29, v3 offset:9904
	ds_write_b16_d16_hi v29, v3 offset:10048
	ds_write_b16 v29, v0 offset:10192
	ds_write_b16_d16_hi v29, v0 offset:10336
	v_or_b32_e32 v0, s20, v24
	v_mov_b64_e32 v[2:3], s[42:43]
	v_mad_u64_u32 v[0:1], s[0:1], v0, s5, v[2:3]
	v_mad_i32_i24 v1, s17, v207, v1
	v_lshl_add_u64 v[0:1], v[0:1], 0, s[38:39]
	v_mov_b32_e32 v61, v33
	v_lshl_add_u64 v[0:1], v[0:1], 0, v[60:61]
	s_lshl_b32 s0, s15, 14
	global_load_dwordx4 v[4:7], v[0:1], off offset:3584
	global_load_dwordx4 v[8:11], v[0:1], off offset:3648
	v_subrev_u32_e32 v0, s0, v63
	v_subrev_u32_e32 v12, 56, v0
	v_ashrrev_i32_e32 v13, 31, v12
	v_lshlrev_b64 v[12:13], 7, v[12:13]
	v_lshl_add_u64 v[16:17], v[44:45], 0, v[12:13]
	v_lshl_add_u64 v[66:67], v[46:47], 0, v[12:13]
	global_load_dwordx4 v[12:15], v[16:17], off offset:16
	s_nop 0
	global_load_dwordx4 v[16:19], v[16:17], off
	s_nop 0
	global_load_dwordx4 v[20:23], v[66:67], off offset:16
; #define LAS __attribute__((address_space(3)))
; __device__ __forceinline__ void retkv_item(const bf16_t* hbuf, const float* rot, float* kvbuf, LAS bf16_t* wl, int item, int lane) {
;     ...
;     { const int cr = lane >> 3, dc = lane & 7, fc = dc & 3;
; #pragma unroll
;       for (int i = 0; i < 8; ++i) { const int row = cr + 8 * i; const bf16_t* kp = hbuf + (t0 + row) * INWP + C_RK + h * 64;
;           const u32x4 x1 = *(const u32x4*)(kp + 8 * fc), x2 = *(const u32x4*)(kp + 32 + 8 * fc);
;           const int pos = n * 64 + row; u32x4 o1, o2;
;           rot8(x1, x2, rot + (size_t)pos * 32 + 8 * fc, rot + 16384 * 32 + (size_t)pos * 32 + 8 * fc, 0.125f, o1, o2);
;           const u32x4 w = dc < 4 ? o1 : o2;
;           LAS bf16_t* t = kT + (8 * dc) * TLD + row;
;           t[0 * TLD] = (bf16_t)(w.x & 0xffff); t[1 * TLD] = (bf16_t)(w.x >> 16); t[2 * TLD] = (bf16_t)(w.y & 0xffff); t[3 * TLD] = (bf16_t)(w.y >> 16);
;           t[4 * TLD] = (bf16_t)(w.z & 0xffff); t[5 * TLD] = (bf16_t)(w.z >> 16); t[6 * TLD] = (bf16_t)(w.w & 0xffff); t[7 * TLD] = (bf16_t)(w.w >> 16); } }
	s_nop 0
	global_load_dwordx4 v[66:69], v[66:67], off
	v_add_u32_e32 v63, s12, v63
	v_or_b32_e32 v172, s20, v26
	v_mad_u64_u32 v[174:175], s[100:101], v172, s5, v[2:3]
	v_mad_i32_i24 v175, s17, v207, v175
	v_lshl_add_u64 v[174:175], v[174:175], 0, s[38:39]
	v_lshl_add_u64 v[174:175], v[174:175], 0, v[60:61]
	v_subrev_u32_e32 v176, 48, v0
	v_ashrrev_i32_e32 v177, 31, v176
	v_lshlrev_b64 v[176:177], 7, v[176:177]
	v_lshl_add_u64 v[178:179], v[44:45], 0, v[176:177]
	v_lshl_add_u64 v[180:181], v[46:47], 0, v[176:177]
	global_load_dwordx4 v[116:119], v[174:175], off offset:3584
	global_load_dwordx4 v[120:123], v[174:175], off offset:3648
	global_load_dwordx4 v[124:127], v[178:179], off offset:16
	global_load_dwordx4 v[128:131], v[178:179], off
	global_load_dwordx4 v[132:135], v[180:181], off offset:16
	global_load_dwordx4 v[136:139], v[180:181], off
	v_or_b32_e32 v172, s20, v28
	v_mad_u64_u32 v[174:175], s[100:101], v172, s5, v[2:3]
	v_mad_i32_i24 v175, s17, v207, v175
	v_lshl_add_u64 v[174:175], v[174:175], 0, s[38:39]
	v_lshl_add_u64 v[174:175], v[174:175], 0, v[60:61]
	v_subrev_u32_e32 v176, 40, v0
	v_ashrrev_i32_e32 v177, 31, v176
	v_lshlrev_b64 v[176:177], 7, v[176:177]
	v_lshl_add_u64 v[178:179], v[44:45], 0, v[176:177]
	v_lshl_add_u64 v[180:181], v[46:47], 0, v[176:177]
	global_load_dwordx4 v[140:143], v[174:175], off offset:3584
	global_load_dwordx4 v[144:147], v[174:175], off offset:3648
	global_load_dwordx4 v[148:151], v[178:179], off offset:16
	global_load_dwordx4 v[152:155], v[178:179], off
	global_load_dwordx4 v[156:159], v[180:181], off offset:16
	global_load_dwordx4 v[160:163], v[180:181], off
	s_waitcnt vmcnt(17)
	v_lshlrev_b32_e32 v71, 16, v4
	s_waitcnt vmcnt(16)
	v_lshlrev_b32_e32 v70, 16, v8
	s_waitcnt vmcnt(14)
	v_mov_b32_e32 v73, v16
	s_waitcnt vmcnt(12)
	v_mov_b32_e32 v72, v66
	v_pk_mul_f32 v[72:73], v[72:73], v[70:71]
	s_nop 0
	v_sub_f32_e32 v1, v73, v72
	v_mov_b32_e32 v72, v16
	v_mov_b32_e32 v73, v66
	v_pk_mul_f32 v[70:71], v[72:73], v[70:71]
	v_mov_b32_e32 v66, v17
	v_add_f32_e32 v16, v70, v71
	v_mul_f32_e32 v51, 0x3e000000, v16
	v_and_b32_e32 v71, 0xffff0000, v4
	v_and_b32_e32 v70, 0xffff0000, v8
	v_mov_b32_e32 v16, v67
	v_pk_mul_f32 v[72:73], v[16:17], v[70:71]
	v_pk_mul_f32 v[16:17], v[66:67], v[70:71]
	v_sub_f32_e32 v4, v73, v72
	v_mul_f32_e32 v53, 0x3e000000, v4
	v_add_f32_e32 v4, v16, v17
	v_lshlrev_b32_e32 v17, 16, v5
	v_lshlrev_b32_e32 v16, 16, v9
	v_mov_b32_e32 v66, v68
	v_mov_b32_e32 v67, v18
	v_pk_mul_f32 v[66:67], v[66:67], v[16:17]
	v_mul_f32_e32 v55, 0x3e000000, v4
	v_sub_f32_e32 v4, v67, v66
	v_mov_b32_e32 v66, v18
	v_mov_b32_e32 v67, v68
	v_pk_mul_f32 v[16:17], v[66:67], v[16:17]
	v_mul_f32_e32 v57, 0x3e000000, v4
	v_add_f32_e32 v4, v16, v17
	v_mul_f32_e32 v16, 0x3e000000, v4
	v_and_b32_e32 v5, 0xffff0000, v5
	v_and_b32_e32 v4, 0xffff0000, v9
	v_mov_b32_e32 v18, v69
	v_mov_b32_e32 v68, v19
	v_pk_mul_f32 v[8:9], v[18:19], v[4:5]
	v_pk_mul_f32 v[4:5], v[68:69], v[4:5]
	v_sub_f32_e32 v8, v9, v8
	v_add_f32_e32 v4, v4, v5
	v_mul_f32_e32 v17, 0x3e000000, v8
	v_mul_f32_e32 v18, 0x3e000000, v4
	v_lshlrev_b32_e32 v5, 16, v6
	v_lshlrev_b32_e32 v4, 16, v10
	v_mov_b32_e32 v8, v20
	v_mov_b32_e32 v9, v12
	v_pk_mul_f32 v[8:9], v[8:9], v[4:5]
	v_mul_f32_e32 v1, 0x3e000000, v1
	v_sub_f32_e32 v8, v9, v8
	v_mul_f32_e32 v19, 0x3e000000, v8
	v_mov_b32_e32 v8, v12
	v_mov_b32_e32 v9, v20
	v_pk_mul_f32 v[4:5], v[8:9], v[4:5]
	v_mov_b32_e32 v12, v21
	v_add_f32_e32 v4, v4, v5
	v_mul_f32_e32 v59, 0x3e000000, v4
	v_and_b32_e32 v5, 0xffff0000, v6
	v_and_b32_e32 v4, 0xffff0000, v10
	v_mov_b32_e32 v20, v13
	v_pk_mul_f32 v[8:9], v[12:13], v[4:5]
	v_pk_mul_f32 v[4:5], v[20:21], v[4:5]
	v_sub_f32_e32 v6, v9, v8
	v_add_f32_e32 v4, v4, v5
	v_mul_f32_e32 v12, 0x3e000000, v4
	v_lshlrev_b32_e32 v5, 16, v7
	v_lshlrev_b32_e32 v4, 16, v11
	v_mov_b32_e32 v8, v22
	v_mov_b32_e32 v9, v14
	v_pk_mul_f32 v[8:9], v[8:9], v[4:5]
	v_mul_f32_e32 v10, 0x3e000000, v6
	v_sub_f32_e32 v6, v9, v8
	v_mov_b32_e32 v8, v14
	v_mov_b32_e32 v9, v22
	v_pk_mul_f32 v[4:5], v[8:9], v[4:5]
	v_mov_b32_e32 v14, v23
	v_add_f32_e32 v4, v4, v5
	v_mul_f32_e32 v8, 0x3e000000, v4
	v_and_b32_e32 v5, 0xffff0000, v7
	v_and_b32_e32 v4, 0xffff0000, v11
	v_mov_b32_e32 v22, v15
	v_mul_f32_e32 v13, 0x3e000000, v6
	v_pk_mul_f32 v[6:7], v[14:15], v[4:5]
	v_pk_mul_f32 v[4:5], v[22:23], v[4:5]
	v_sub_f32_e32 v6, v7, v6
	v_add_f32_e32 v4, v4, v5
	v_mul_f32_e32 v6, 0x3e000000, v6
	v_mul_f32_e32 v4, 0x3e000000, v4
	v_cvt_pk_bf16_f32 v1, v1, v53
	v_cvt_pk_bf16_f32 v5, v57, v17
	v_cvt_pk_bf16_f32 v6, v13, v6
	v_cvt_pk_bf16_f32 v9, v51, v55
	v_cvt_pk_bf16_f32 v4, v8, v4
	v_cvt_pk_bf16_f32 v7, v19, v10
	v_cvt_pk_bf16_f32 v10, v16, v18
	v_cvt_pk_bf16_f32 v11, v59, v12
	v_subrev_u32_e32 v12, 48, v0
	v_cndmask_b32_e32 v1, v9, v1, vcc
	v_cndmask_b32_e32 v4, v4, v6, vcc
	v_cndmask_b32_e32 v6, v11, v7, vcc
	v_cndmask_b32_e32 v5, v10, v5, vcc
	ds_write_b16 v29, v1
	ds_write_b16_d16_hi v29, v1 offset:144
	ds_write_b16 v29, v5 offset:288
	ds_write_b16_d16_hi v29, v5 offset:432
	ds_write_b16 v29, v6 offset:576
	ds_write_b16_d16_hi v29, v6 offset:720
	ds_write_b16 v29, v4 offset:864
	ds_write_b16_d16_hi v29, v4 offset:1008
	v_or_b32_e32 v1, s20, v26
	v_mad_u64_u32 v[4:5], s[0:1], v1, s5, v[2:3]
	v_mad_i32_i24 v5, s17, v207, v5
	v_ashrrev_i32_e32 v13, 31, v12
	v_lshl_add_u64 v[4:5], v[4:5], 0, s[38:39]
	v_lshlrev_b64 v[12:13], 7, v[12:13]
	v_lshl_add_u64 v[8:9], v[4:5], 0, v[60:61]
	v_lshl_add_u64 v[16:17], v[44:45], 0, v[12:13]
	v_lshl_add_u64 v[66:67], v[46:47], 0, v[12:13]
	s_nop 0
	s_nop 0
	s_nop 0
	s_nop 0
	s_nop 0
	s_waitcnt vmcnt(6)
; #define LAS __attribute__((address_space(3)))
; __device__ __forceinline__ void retkv_item(const bf16_t* hbuf, const float* rot, float* kvbuf, LAS bf16_t* wl, int item, int lane) {
;     ...
;     { const int cr = lane >> 3, dc = lane & 7, fc = dc & 3;
; #pragma unroll
;       for (int i = 0; i < 8; ++i) { const int row = cr + 8 * i; const bf16_t* kp = hbuf + (t0 + row) * INWP + C_RK + h * 64;
;           const u32x4 x1 = *(const u32x4*)(kp + 8 * fc), x2 = *(const u32x4*)(kp + 32 + 8 * fc);
;           const int pos = n * 64 + row; u32x4 o1, o2;
;           rot8(x1, x2, rot + (size_t)pos * 32 + 8 * fc, rot + 16384 * 32 + (size_t)pos * 32 + 8 * fc, 0.125f, o1, o2);
;           const u32x4 w = dc < 4 ? o1 : o2;
;           LAS bf16_t* t = kT + (8 * dc) * TLD + row;
;           t[0 * TLD] = (bf16_t)(w.x & 0xffff); t[1 * TLD] = (bf16_t)(w.x >> 16); t[2 * TLD] = (bf16_t)(w.y & 0xffff); t[3 * TLD] = (bf16_t)(w.y >> 16);
;           t[4 * TLD] = (bf16_t)(w.z & 0xffff); t[5 * TLD] = (bf16_t)(w.z >> 16); t[6 * TLD] = (bf16_t)(w.w & 0xffff); t[7 * TLD] = (bf16_t)(w.w >> 16); } }
	v_mov_b32_e32 v4, v116
	v_mov_b32_e32 v5, v117
	v_mov_b32_e32 v6, v118
	v_mov_b32_e32 v7, v119
	v_mov_b32_e32 v8, v120
	v_mov_b32_e32 v9, v121
	v_mov_b32_e32 v10, v122
	v_mov_b32_e32 v11, v123
	v_mov_b32_e32 v12, v124
	v_mov_b32_e32 v13, v125
	v_mov_b32_e32 v14, v126
	v_mov_b32_e32 v15, v127
	v_mov_b32_e32 v16, v128
	v_mov_b32_e32 v17, v129
	v_mov_b32_e32 v18, v130
	v_mov_b32_e32 v19, v131
	v_mov_b32_e32 v20, v132
	v_mov_b32_e32 v21, v133
	v_mov_b32_e32 v22, v134
	v_mov_b32_e32 v23, v135
	v_mov_b32_e32 v66, v136
	v_mov_b32_e32 v67, v137
	v_mov_b32_e32 v68, v138
	v_mov_b32_e32 v69, v139
	v_or_b32_e32 v172, s20, v30
	v_mad_u64_u32 v[174:175], s[100:101], v172, s5, v[2:3]
	v_mad_i32_i24 v175, s17, v207, v175
	v_lshl_add_u64 v[174:175], v[174:175], 0, s[38:39]
	v_lshl_add_u64 v[174:175], v[174:175], 0, v[60:61]
	v_subrev_u32_e32 v176, 32, v0
	v_ashrrev_i32_e32 v177, 31, v176
	v_lshlrev_b64 v[176:177], 7, v[176:177]
	v_lshl_add_u64 v[178:179], v[44:45], 0, v[176:177]
	v_lshl_add_u64 v[180:181], v[46:47], 0, v[176:177]
	global_load_dwordx4 v[92:95], v[174:175], off offset:3584
	global_load_dwordx4 v[96:99], v[174:175], off offset:3648
	global_load_dwordx4 v[100:103], v[178:179], off offset:16
	global_load_dwordx4 v[104:107], v[178:179], off
	global_load_dwordx4 v[108:111], v[180:181], off offset:16
	global_load_dwordx4 v[112:115], v[180:181], off
	v_lshlrev_b32_e32 v71, 16, v4
	v_lshlrev_b32_e32 v70, 16, v8
	v_mov_b32_e32 v72, v66
	v_mov_b32_e32 v73, v16
	v_pk_mul_f32 v[72:73], v[72:73], v[70:71]
	s_nop 0
	v_sub_f32_e32 v1, v73, v72
	v_mov_b32_e32 v72, v16
	v_mov_b32_e32 v73, v66
	v_pk_mul_f32 v[70:71], v[72:73], v[70:71]
	v_mov_b32_e32 v66, v17
	v_add_f32_e32 v16, v70, v71
	v_mul_f32_e32 v51, 0x3e000000, v16
	v_and_b32_e32 v71, 0xffff0000, v4
	v_and_b32_e32 v70, 0xffff0000, v8
	v_mov_b32_e32 v16, v67
	v_pk_mul_f32 v[72:73], v[16:17], v[70:71]
	v_pk_mul_f32 v[16:17], v[66:67], v[70:71]
	v_sub_f32_e32 v4, v73, v72
	v_mul_f32_e32 v53, 0x3e000000, v4
	v_add_f32_e32 v4, v16, v17
	v_lshlrev_b32_e32 v17, 16, v5
	v_lshlrev_b32_e32 v16, 16, v9
	v_mov_b32_e32 v66, v68
	v_mov_b32_e32 v67, v18
	v_pk_mul_f32 v[66:67], v[66:67], v[16:17]
	v_mul_f32_e32 v55, 0x3e000000, v4
	v_sub_f32_e32 v4, v67, v66
	v_mov_b32_e32 v66, v18
	v_mov_b32_e32 v67, v68
	v_pk_mul_f32 v[16:17], v[66:67], v[16:17]
	v_mul_f32_e32 v57, 0x3e000000, v4
	v_add_f32_e32 v4, v16, v17
	v_mul_f32_e32 v16, 0x3e000000, v4
	v_and_b32_e32 v5, 0xffff0000, v5
	v_and_b32_e32 v4, 0xffff0000, v9
	v_mov_b32_e32 v18, v69
	v_mov_b32_e32 v68, v19
	v_pk_mul_f32 v[8:9], v[18:19], v[4:5]
	v_pk_mul_f32 v[4:5], v[68:69], v[4:5]
	v_sub_f32_e32 v8, v9, v8
	v_add_f32_e32 v4, v4, v5
	v_mul_f32_e32 v17, 0x3e000000, v8
	v_mul_f32_e32 v18, 0x3e000000, v4
	v_lshlrev_b32_e32 v5, 16, v6
	v_lshlrev_b32_e32 v4, 16, v10
	v_mov_b32_e32 v8, v20
	v_mov_b32_e32 v9, v12
	v_pk_mul_f32 v[8:9], v[8:9], v[4:5]
	v_mul_f32_e32 v1, 0x3e000000, v1
	v_sub_f32_e32 v8, v9, v8
	v_mul_f32_e32 v19, 0x3e000000, v8
	v_mov_b32_e32 v8, v12
	v_mov_b32_e32 v9, v20
	v_pk_mul_f32 v[4:5], v[8:9], v[4:5]
	v_mov_b32_e32 v12, v21
	v_add_f32_e32 v4, v4, v5
	v_mul_f32_e32 v59, 0x3e000000, v4
	v_and_b32_e32 v5, 0xffff0000, v6
	v_and_b32_e32 v4, 0xffff0000, v10
	v_mov_b32_e32 v20, v13
	v_pk_mul_f32 v[8:9], v[12:13], v[4:5]
	v_pk_mul_f32 v[4:5], v[20:21], v[4:5]
	v_sub_f32_e32 v6, v9, v8
	v_add_f32_e32 v4, v4, v5
	v_mul_f32_e32 v12, 0x3e000000, v4
	v_lshlrev_b32_e32 v5, 16, v7
	v_lshlrev_b32_e32 v4, 16, v11
	v_mov_b32_e32 v8, v22
	v_mov_b32_e32 v9, v14
	v_pk_mul_f32 v[8:9], v[8:9], v[4:5]
	v_mul_f32_e32 v10, 0x3e000000, v6
	v_sub_f32_e32 v6, v9, v8
	v_mov_b32_e32 v8, v14
	v_mov_b32_e32 v9, v22
	v_pk_mul_f32 v[4:5], v[8:9], v[4:5]
	v_mov_b32_e32 v14, v23
	v_add_f32_e32 v4, v4, v5
	v_mul_f32_e32 v8, 0x3e000000, v4
	v_and_b32_e32 v5, 0xffff0000, v7
	v_and_b32_e32 v4, 0xffff0000, v11
	v_mov_b32_e32 v22, v15
	v_mul_f32_e32 v13, 0x3e000000, v6
	v_pk_mul_f32 v[6:7], v[14:15], v[4:5]
	v_pk_mul_f32 v[4:5], v[22:23], v[4:5]
	v_sub_f32_e32 v6, v7, v6
	v_add_f32_e32 v4, v4, v5
	v_mul_f32_e32 v6, 0x3e000000, v6
	v_mul_f32_e32 v4, 0x3e000000, v4
	v_cvt_pk_bf16_f32 v1, v1, v53
	v_cvt_pk_bf16_f32 v5, v57, v17
	v_cvt_pk_bf16_f32 v6, v13, v6
	v_cvt_pk_bf16_f32 v9, v51, v55
	v_cvt_pk_bf16_f32 v4, v8, v4
	v_cvt_pk_bf16_f32 v7, v19, v10
	v_cvt_pk_bf16_f32 v10, v16, v18
	v_cvt_pk_bf16_f32 v11, v59, v12
	v_subrev_u32_e32 v12, 40, v0
	v_cndmask_b32_e32 v1, v9, v1, vcc
	v_cndmask_b32_e32 v4, v4, v6, vcc
	v_cndmask_b32_e32 v6, v11, v7, vcc
	v_cndmask_b32_e32 v5, v10, v5, vcc
	ds_write_b16 v29, v1 offset:16
	ds_write_b16_d16_hi v29, v1 offset:160
	ds_write_b16 v29, v5 offset:304
	ds_write_b16_d16_hi v29, v5 offset:448
	ds_write_b16 v29, v6 offset:592
	ds_write_b16_d16_hi v29, v6 offset:736
	ds_write_b16 v29, v4 offset:880
	ds_write_b16_d16_hi v29, v4 offset:1024
	v_or_b32_e32 v1, s20, v28
	v_mad_u64_u32 v[4:5], s[0:1], v1, s5, v[2:3]
	v_mad_i32_i24 v5, s17, v207, v5
	v_ashrrev_i32_e32 v13, 31, v12
	v_lshl_add_u64 v[4:5], v[4:5], 0, s[38:39]
	v_lshlrev_b64 v[12:13], 7, v[12:13]
	v_lshl_add_u64 v[8:9], v[4:5], 0, v[60:61]
	v_lshl_add_u64 v[16:17], v[44:45], 0, v[12:13]
	v_lshl_add_u64 v[66:67], v[46:47], 0, v[12:13]
	s_nop 0
	s_nop 0
	s_nop 0
	s_nop 0
	s_nop 0
	s_waitcnt vmcnt(6)
; #define LAS __attribute__((address_space(3)))
; __device__ __forceinline__ void retkv_item(const bf16_t* hbuf, const float* rot, float* kvbuf, LAS bf16_t* wl, int item, int lane) {
;     ...
;     { const int cr = lane >> 3, dc = lane & 7, fc = dc & 3;
; #pragma unroll
;       for (int i = 0; i < 8; ++i) { const int row = cr + 8 * i; const bf16_t* kp = hbuf + (t0 + row) * INWP + C_RK + h * 64;
;           const u32x4 x1 = *(const u32x4*)(kp + 8 * fc), x2 = *(const u32x4*)(kp + 32 + 8 * fc);
;           const int pos = n * 64 + row; u32x4 o1, o2;
;           rot8(x1, x2, rot + (size_t)pos * 32 + 8 * fc, rot + 16384 * 32 + (size_t)pos * 32 + 8 * fc, 0.125f, o1, o2);
;           const u32x4 w = dc < 4 ? o1 : o2;
;           LAS bf16_t* t = kT + (8 * dc) * TLD + row;
;           t[0 * TLD] = (bf16_t)(w.x & 0xffff); t[1 * TLD] = (bf16_t)(w.x >> 16); t[2 * TLD] = (bf16_t)(w.y & 0xffff); t[3 * TLD] = (bf16_t)(w.y >> 16);
;           t[4 * TLD] = (bf16_t)(w.z & 0xffff); t[5 * TLD] = (bf16_t)(w.z >> 16); t[6 * TLD] = (bf16_t)(w.w & 0xffff); t[7 * TLD] = (bf16_t)(w.w >> 16); } }
	v_mov_b32_e32 v4, v140
	v_mov_b32_e32 v5, v141
	v_mov_b32_e32 v6, v142
	v_mov_b32_e32 v7, v143
	v_mov_b32_e32 v8, v144
	v_mov_b32_e32 v9, v145
	v_mov_b32_e32 v10, v146
	v_mov_b32_e32 v11, v147
	v_mov_b32_e32 v12, v148
	v_mov_b32_e32 v13, v149
	v_mov_b32_e32 v14, v150
	v_mov_b32_e32 v15, v151
	v_mov_b32_e32 v16, v152
	v_mov_b32_e32 v17, v153
	v_mov_b32_e32 v18, v154
	v_mov_b32_e32 v19, v155
	v_mov_b32_e32 v20, v156
	v_mov_b32_e32 v21, v157
	v_mov_b32_e32 v22, v158
	v_mov_b32_e32 v23, v159
	v_mov_b32_e32 v66, v160
	v_mov_b32_e32 v67, v161
	v_mov_b32_e32 v68, v162
	v_mov_b32_e32 v69, v163
	v_or_b32_e32 v172, s20, v34
	v_mad_u64_u32 v[174:175], s[100:101], v172, s5, v[2:3]
	v_mad_i32_i24 v175, s17, v207, v175
	v_lshl_add_u64 v[174:175], v[174:175], 0, s[38:39]
	v_lshl_add_u64 v[174:175], v[174:175], 0, v[60:61]
	v_subrev_u32_e32 v176, 24, v0
	v_ashrrev_i32_e32 v177, 31, v176
	v_lshlrev_b64 v[176:177], 7, v[176:177]
	v_lshl_add_u64 v[178:179], v[44:45], 0, v[176:177]
	v_lshl_add_u64 v[180:181], v[46:47], 0, v[176:177]
	global_load_dwordx4 v[116:119], v[174:175], off offset:3584
	global_load_dwordx4 v[120:123], v[174:175], off offset:3648
	global_load_dwordx4 v[124:127], v[178:179], off offset:16
	global_load_dwordx4 v[128:131], v[178:179], off
	global_load_dwordx4 v[132:135], v[180:181], off offset:16
	global_load_dwordx4 v[136:139], v[180:181], off
	v_lshlrev_b32_e32 v71, 16, v4
	v_lshlrev_b32_e32 v70, 16, v8
	v_mov_b32_e32 v72, v66
	v_mov_b32_e32 v73, v16
	v_pk_mul_f32 v[72:73], v[72:73], v[70:71]
	s_nop 0
	v_sub_f32_e32 v1, v73, v72
	v_mov_b32_e32 v72, v16
	v_mov_b32_e32 v73, v66
	v_pk_mul_f32 v[70:71], v[72:73], v[70:71]
	v_mov_b32_e32 v66, v17
	v_add_f32_e32 v16, v70, v71
	v_mul_f32_e32 v51, 0x3e000000, v16
	v_and_b32_e32 v71, 0xffff0000, v4
	v_and_b32_e32 v70, 0xffff0000, v8
	v_mov_b32_e32 v16, v67
	v_pk_mul_f32 v[72:73], v[16:17], v[70:71]
	v_pk_mul_f32 v[16:17], v[66:67], v[70:71]
	v_sub_f32_e32 v4, v73, v72
	v_mul_f32_e32 v53, 0x3e000000, v4
	v_add_f32_e32 v4, v16, v17
	v_lshlrev_b32_e32 v17, 16, v5
	v_lshlrev_b32_e32 v16, 16, v9
	v_mov_b32_e32 v66, v68
	v_mov_b32_e32 v67, v18
	v_pk_mul_f32 v[66:67], v[66:67], v[16:17]
	v_mul_f32_e32 v55, 0x3e000000, v4
	v_sub_f32_e32 v4, v67, v66
	v_mov_b32_e32 v66, v18
	v_mov_b32_e32 v67, v68
	v_pk_mul_f32 v[16:17], v[66:67], v[16:17]
	v_mul_f32_e32 v57, 0x3e000000, v4
	v_add_f32_e32 v4, v16, v17
	v_mul_f32_e32 v16, 0x3e000000, v4
	v_and_b32_e32 v5, 0xffff0000, v5
	v_and_b32_e32 v4, 0xffff0000, v9
	v_mov_b32_e32 v18, v69
	v_mov_b32_e32 v68, v19
	v_pk_mul_f32 v[8:9], v[18:19], v[4:5]
	v_pk_mul_f32 v[4:5], v[68:69], v[4:5]
	v_sub_f32_e32 v8, v9, v8
	v_add_f32_e32 v4, v4, v5
	v_mul_f32_e32 v17, 0x3e000000, v8
	v_mul_f32_e32 v18, 0x3e000000, v4
	v_lshlrev_b32_e32 v5, 16, v6
	v_lshlrev_b32_e32 v4, 16, v10
	v_mov_b32_e32 v8, v20
	v_mov_b32_e32 v9, v12
	v_pk_mul_f32 v[8:9], v[8:9], v[4:5]
	v_mul_f32_e32 v1, 0x3e000000, v1
	v_sub_f32_e32 v8, v9, v8
	v_mul_f32_e32 v19, 0x3e000000, v8
	v_mov_b32_e32 v8, v12
	v_mov_b32_e32 v9, v20
	v_pk_mul_f32 v[4:5], v[8:9], v[4:5]
	v_mov_b32_e32 v12, v21
	v_add_f32_e32 v4, v4, v5
	v_mul_f32_e32 v59, 0x3e000000, v4
	v_and_b32_e32 v5, 0xffff0000, v6
	v_and_b32_e32 v4, 0xffff0000, v10
	v_mov_b32_e32 v20, v13
	v_pk_mul_f32 v[8:9], v[12:13], v[4:5]
	v_pk_mul_f32 v[4:5], v[20:21], v[4:5]
	v_sub_f32_e32 v6, v9, v8
	v_add_f32_e32 v4, v4, v5
	v_mul_f32_e32 v12, 0x3e000000, v4
	v_lshlrev_b32_e32 v5, 16, v7
	v_lshlrev_b32_e32 v4, 16, v11
	v_mov_b32_e32 v8, v22
	v_mov_b32_e32 v9, v14
	v_pk_mul_f32 v[8:9], v[8:9], v[4:5]
	v_mul_f32_e32 v10, 0x3e000000, v6
	v_sub_f32_e32 v6, v9, v8
	v_mov_b32_e32 v8, v14
	v_mov_b32_e32 v9, v22
	v_pk_mul_f32 v[4:5], v[8:9], v[4:5]
	v_mov_b32_e32 v14, v23
	v_add_f32_e32 v4, v4, v5
	v_mul_f32_e32 v8, 0x3e000000, v4
	v_and_b32_e32 v5, 0xffff0000, v7
	v_and_b32_e32 v4, 0xffff0000, v11
	v_mov_b32_e32 v22, v15
	v_mul_f32_e32 v13, 0x3e000000, v6
	v_pk_mul_f32 v[6:7], v[14:15], v[4:5]
	v_pk_mul_f32 v[4:5], v[22:23], v[4:5]
	v_sub_f32_e32 v6, v7, v6
	v_add_f32_e32 v4, v4, v5
	v_mul_f32_e32 v6, 0x3e000000, v6
	v_mul_f32_e32 v4, 0x3e000000, v4
	v_cvt_pk_bf16_f32 v1, v1, v53
	v_cvt_pk_bf16_f32 v5, v57, v17
	v_cvt_pk_bf16_f32 v6, v13, v6
	v_cvt_pk_bf16_f32 v9, v51, v55
	v_cvt_pk_bf16_f32 v4, v8, v4
	v_cvt_pk_bf16_f32 v7, v19, v10
	v_cvt_pk_bf16_f32 v10, v16, v18
	v_cvt_pk_bf16_f32 v11, v59, v12
	v_subrev_u32_e32 v12, 32, v0
	v_cndmask_b32_e32 v1, v9, v1, vcc
	v_cndmask_b32_e32 v4, v4, v6, vcc
	v_cndmask_b32_e32 v6, v11, v7, vcc
	v_cndmask_b32_e32 v5, v10, v5, vcc
	ds_write_b16 v29, v1 offset:32
	ds_write_b16_d16_hi v29, v1 offset:176
	ds_write_b16 v29, v5 offset:320
	ds_write_b16_d16_hi v29, v5 offset:464
	ds_write_b16 v29, v6 offset:608
	ds_write_b16_d16_hi v29, v6 offset:752
	ds_write_b16 v29, v4 offset:896
	ds_write_b16_d16_hi v29, v4 offset:1040
	v_or_b32_e32 v1, s20, v30
	v_mad_u64_u32 v[4:5], s[0:1], v1, s5, v[2:3]
	v_mad_i32_i24 v5, s17, v207, v5
	v_ashrrev_i32_e32 v13, 31, v12
	v_lshl_add_u64 v[4:5], v[4:5], 0, s[38:39]
	v_lshlrev_b64 v[12:13], 7, v[12:13]
	v_lshl_add_u64 v[8:9], v[4:5], 0, v[60:61]
	v_lshl_add_u64 v[16:17], v[44:45], 0, v[12:13]
	v_lshl_add_u64 v[66:67], v[46:47], 0, v[12:13]
	s_nop 0
	s_nop 0
	s_nop 0
	s_nop 0
	s_nop 0
	s_waitcnt vmcnt(6)
; #define LAS __attribute__((address_space(3)))
; __device__ __forceinline__ void retkv_item(const bf16_t* hbuf, const float* rot, float* kvbuf, LAS bf16_t* wl, int item, int lane) {
;     ...
;     { const int cr = lane >> 3, dc = lane & 7, fc = dc & 3;
; #pragma unroll
;       for (int i = 0; i < 8; ++i) { const int row = cr + 8 * i; const bf16_t* kp = hbuf + (t0 + row) * INWP + C_RK + h * 64;
;           const u32x4 x1 = *(const u32x4*)(kp + 8 * fc), x2 = *(const u32x4*)(kp + 32 + 8 * fc);
;           const int pos = n * 64 + row; u32x4 o1, o2;
;           rot8(x1, x2, rot + (size_t)pos * 32 + 8 * fc, rot + 16384 * 32 + (size_t)pos * 32 + 8 * fc, 0.125f, o1, o2);
;           const u32x4 w = dc < 4 ? o1 : o2;
;           LAS bf16_t* t = kT + (8 * dc) * TLD + row;
;           t[0 * TLD] = (bf16_t)(w.x & 0xffff); t[1 * TLD] = (bf16_t)(w.x >> 16); t[2 * TLD] = (bf16_t)(w.y & 0xffff); t[3 * TLD] = (bf16_t)(w.y >> 16);
;           t[4 * TLD] = (bf16_t)(w.z & 0xffff); t[5 * TLD] = (bf16_t)(w.z >> 16); t[6 * TLD] = (bf16_t)(w.w & 0xffff); t[7 * TLD] = (bf16_t)(w.w >> 16); } }
	v_mov_b32_e32 v4, v92
	v_mov_b32_e32 v5, v93
	v_mov_b32_e32 v6, v94
	v_mov_b32_e32 v7, v95
	v_mov_b32_e32 v8, v96
	v_mov_b32_e32 v9, v97
	v_mov_b32_e32 v10, v98
	v_mov_b32_e32 v11, v99
	v_mov_b32_e32 v12, v100
	v_mov_b32_e32 v13, v101
	v_mov_b32_e32 v14, v102
	v_mov_b32_e32 v15, v103
	v_mov_b32_e32 v16, v104
	v_mov_b32_e32 v17, v105
	v_mov_b32_e32 v18, v106
	v_mov_b32_e32 v19, v107
	v_mov_b32_e32 v20, v108
	v_mov_b32_e32 v21, v109
	v_mov_b32_e32 v22, v110
	v_mov_b32_e32 v23, v111
	v_mov_b32_e32 v66, v112
	v_mov_b32_e32 v67, v113
	v_mov_b32_e32 v68, v114
	v_mov_b32_e32 v69, v115
	v_or_b32_e32 v172, s20, v36
	v_mad_u64_u32 v[174:175], s[100:101], v172, s5, v[2:3]
	v_mad_i32_i24 v175, s17, v207, v175
	v_lshl_add_u64 v[174:175], v[174:175], 0, s[38:39]
	v_lshl_add_u64 v[174:175], v[174:175], 0, v[60:61]
	v_subrev_u32_e32 v176, 16, v0
	v_ashrrev_i32_e32 v177, 31, v176
	v_lshlrev_b64 v[176:177], 7, v[176:177]
	v_lshl_add_u64 v[178:179], v[44:45], 0, v[176:177]
	v_lshl_add_u64 v[180:181], v[46:47], 0, v[176:177]
	global_load_dwordx4 v[140:143], v[174:175], off offset:3584
	global_load_dwordx4 v[144:147], v[174:175], off offset:3648
	global_load_dwordx4 v[148:151], v[178:179], off offset:16
	global_load_dwordx4 v[152:155], v[178:179], off
	global_load_dwordx4 v[156:159], v[180:181], off offset:16
	global_load_dwordx4 v[160:163], v[180:181], off
	v_lshlrev_b32_e32 v71, 16, v4
	v_lshlrev_b32_e32 v70, 16, v8
	v_mov_b32_e32 v72, v66
	v_mov_b32_e32 v73, v16
	v_pk_mul_f32 v[72:73], v[72:73], v[70:71]
	s_nop 0
	v_sub_f32_e32 v1, v73, v72
	v_mov_b32_e32 v72, v16
	v_mov_b32_e32 v73, v66
	v_pk_mul_f32 v[70:71], v[72:73], v[70:71]
	v_mov_b32_e32 v66, v17
	v_add_f32_e32 v16, v70, v71
	v_mul_f32_e32 v51, 0x3e000000, v16
	v_and_b32_e32 v71, 0xffff0000, v4
	v_and_b32_e32 v70, 0xffff0000, v8
	v_mov_b32_e32 v16, v67
	v_pk_mul_f32 v[72:73], v[16:17], v[70:71]
	v_pk_mul_f32 v[16:17], v[66:67], v[70:71]
	v_sub_f32_e32 v4, v73, v72
	v_mul_f32_e32 v53, 0x3e000000, v4
	v_add_f32_e32 v4, v16, v17
	v_lshlrev_b32_e32 v17, 16, v5
	v_lshlrev_b32_e32 v16, 16, v9
	v_mov_b32_e32 v66, v68
	v_mov_b32_e32 v67, v18
	v_pk_mul_f32 v[66:67], v[66:67], v[16:17]
	v_mul_f32_e32 v55, 0x3e000000, v4
	v_sub_f32_e32 v4, v67, v66
	v_mov_b32_e32 v66, v18
	v_mov_b32_e32 v67, v68
	v_pk_mul_f32 v[16:17], v[66:67], v[16:17]
	v_mul_f32_e32 v57, 0x3e000000, v4
	v_add_f32_e32 v4, v16, v17
	v_mul_f32_e32 v16, 0x3e000000, v4
	v_and_b32_e32 v5, 0xffff0000, v5
	v_and_b32_e32 v4, 0xffff0000, v9
	v_mov_b32_e32 v18, v69
	v_mov_b32_e32 v68, v19
	v_pk_mul_f32 v[8:9], v[18:19], v[4:5]
	v_pk_mul_f32 v[4:5], v[68:69], v[4:5]
	v_sub_f32_e32 v8, v9, v8
	v_add_f32_e32 v4, v4, v5
	v_mul_f32_e32 v17, 0x3e000000, v8
	v_mul_f32_e32 v18, 0x3e000000, v4
	v_lshlrev_b32_e32 v5, 16, v6
	v_lshlrev_b32_e32 v4, 16, v10
	v_mov_b32_e32 v8, v20
	v_mov_b32_e32 v9, v12
	v_pk_mul_f32 v[8:9], v[8:9], v[4:5]
	v_mul_f32_e32 v1, 0x3e000000, v1
	v_sub_f32_e32 v8, v9, v8
	v_mul_f32_e32 v19, 0x3e000000, v8
	v_mov_b32_e32 v8, v12
	v_mov_b32_e32 v9, v20
	v_pk_mul_f32 v[4:5], v[8:9], v[4:5]
	v_mov_b32_e32 v12, v21
	v_add_f32_e32 v4, v4, v5
	v_mul_f32_e32 v59, 0x3e000000, v4
	v_and_b32_e32 v5, 0xffff0000, v6
	v_and_b32_e32 v4, 0xffff0000, v10
	v_mov_b32_e32 v20, v13
	v_pk_mul_f32 v[8:9], v[12:13], v[4:5]
	v_pk_mul_f32 v[4:5], v[20:21], v[4:5]
	v_sub_f32_e32 v6, v9, v8
	v_add_f32_e32 v4, v4, v5
	v_mul_f32_e32 v12, 0x3e000000, v4
	v_lshlrev_b32_e32 v5, 16, v7
	v_lshlrev_b32_e32 v4, 16, v11
	v_mov_b32_e32 v8, v22
	v_mov_b32_e32 v9, v14
	v_pk_mul_f32 v[8:9], v[8:9], v[4:5]
	v_mul_f32_e32 v10, 0x3e000000, v6
	v_sub_f32_e32 v6, v9, v8
	v_mov_b32_e32 v8, v14
	v_mov_b32_e32 v9, v22
	v_pk_mul_f32 v[4:5], v[8:9], v[4:5]
	v_mov_b32_e32 v14, v23
	v_add_f32_e32 v4, v4, v5
	v_mul_f32_e32 v8, 0x3e000000, v4
	v_and_b32_e32 v5, 0xffff0000, v7
	v_and_b32_e32 v4, 0xffff0000, v11
	v_mov_b32_e32 v22, v15
	v_mul_f32_e32 v13, 0x3e000000, v6
	v_pk_mul_f32 v[6:7], v[14:15], v[4:5]
	v_pk_mul_f32 v[4:5], v[22:23], v[4:5]
	v_sub_f32_e32 v6, v7, v6
	v_add_f32_e32 v4, v4, v5
	v_mul_f32_e32 v6, 0x3e000000, v6
	v_mul_f32_e32 v4, 0x3e000000, v4
	v_cvt_pk_bf16_f32 v1, v1, v53
	v_cvt_pk_bf16_f32 v5, v57, v17
	v_cvt_pk_bf16_f32 v6, v13, v6
	v_cvt_pk_bf16_f32 v9, v51, v55
	v_cvt_pk_bf16_f32 v4, v8, v4
	v_cvt_pk_bf16_f32 v7, v19, v10
	v_cvt_pk_bf16_f32 v10, v16, v18
	v_cvt_pk_bf16_f32 v11, v59, v12
	v_subrev_u32_e32 v12, 24, v0
	v_cndmask_b32_e32 v1, v9, v1, vcc
	v_cndmask_b32_e32 v4, v4, v6, vcc
	v_cndmask_b32_e32 v6, v11, v7, vcc
	v_cndmask_b32_e32 v5, v10, v5, vcc
	ds_write_b16 v29, v1 offset:48
	ds_write_b16_d16_hi v29, v1 offset:192
	ds_write_b16 v29, v5 offset:336
	ds_write_b16_d16_hi v29, v5 offset:480
	ds_write_b16 v29, v6 offset:624
	ds_write_b16_d16_hi v29, v6 offset:768
	ds_write_b16 v29, v4 offset:912
	ds_write_b16_d16_hi v29, v4 offset:1056
	v_or_b32_e32 v1, s20, v34
	v_mad_u64_u32 v[4:5], s[0:1], v1, s5, v[2:3]
	v_mad_i32_i24 v5, s17, v207, v5
	v_ashrrev_i32_e32 v13, 31, v12
	v_lshl_add_u64 v[4:5], v[4:5], 0, s[38:39]
	v_lshlrev_b64 v[12:13], 7, v[12:13]
	v_lshl_add_u64 v[8:9], v[4:5], 0, v[60:61]
	v_lshl_add_u64 v[16:17], v[44:45], 0, v[12:13]
	v_lshl_add_u64 v[66:67], v[46:47], 0, v[12:13]
	s_nop 0
	s_nop 0
	s_nop 0
	s_nop 0
	s_nop 0
	s_waitcnt vmcnt(6)
; #define LAS __attribute__((address_space(3)))
; __device__ __forceinline__ void retkv_item(const bf16_t* hbuf, const float* rot, float* kvbuf, LAS bf16_t* wl, int item, int lane) {
;     ...
;     { const int cr = lane >> 3, dc = lane & 7, fc = dc & 3;
; #pragma unroll
;       for (int i = 0; i < 8; ++i) { const int row = cr + 8 * i; const bf16_t* kp = hbuf + (t0 + row) * INWP + C_RK + h * 64;
;           const u32x4 x1 = *(const u32x4*)(kp + 8 * fc), x2 = *(const u32x4*)(kp + 32 + 8 * fc);
;           const int pos = n * 64 + row; u32x4 o1, o2;
;           rot8(x1, x2, rot + (size_t)pos * 32 + 8 * fc, rot + 16384 * 32 + (size_t)pos * 32 + 8 * fc, 0.125f, o1, o2);
;           const u32x4 w = dc < 4 ? o1 : o2;
;           LAS bf16_t* t = kT + (8 * dc) * TLD + row;
;           t[0 * TLD] = (bf16_t)(w.x & 0xffff); t[1 * TLD] = (bf16_t)(w.x >> 16); t[2 * TLD] = (bf16_t)(w.y & 0xffff); t[3 * TLD] = (bf16_t)(w.y >> 16);
;           t[4 * TLD] = (bf16_t)(w.z & 0xffff); t[5 * TLD] = (bf16_t)(w.z >> 16); t[6 * TLD] = (bf16_t)(w.w & 0xffff); t[7 * TLD] = (bf16_t)(w.w >> 16); } }
	v_mov_b32_e32 v4, v116
	v_mov_b32_e32 v5, v117
	v_mov_b32_e32 v6, v118
	v_mov_b32_e32 v7, v119
	v_mov_b32_e32 v8, v120
	v_mov_b32_e32 v9, v121
	v_mov_b32_e32 v10, v122
	v_mov_b32_e32 v11, v123
	v_mov_b32_e32 v12, v124
	v_mov_b32_e32 v13, v125
	v_mov_b32_e32 v14, v126
	v_mov_b32_e32 v15, v127
	v_mov_b32_e32 v16, v128
	v_mov_b32_e32 v17, v129
	v_mov_b32_e32 v18, v130
	v_mov_b32_e32 v19, v131
	v_mov_b32_e32 v20, v132
	v_mov_b32_e32 v21, v133
	v_mov_b32_e32 v22, v134
	v_mov_b32_e32 v23, v135
	v_mov_b32_e32 v66, v136
	v_mov_b32_e32 v67, v137
	v_mov_b32_e32 v68, v138
	v_mov_b32_e32 v69, v139
	v_or_b32_e32 v172, s20, v40
	v_mad_u64_u32 v[174:175], s[100:101], v172, s5, v[2:3]
	v_mad_i32_i24 v175, s17, v207, v175
	v_lshl_add_u64 v[174:175], v[174:175], 0, s[38:39]
	v_lshl_add_u64 v[174:175], v[174:175], 0, v[60:61]
	v_subrev_u32_e32 v176, 8, v0
	v_ashrrev_i32_e32 v177, 31, v176
	v_lshlrev_b64 v[176:177], 7, v[176:177]
	v_lshl_add_u64 v[178:179], v[44:45], 0, v[176:177]
	v_lshl_add_u64 v[180:181], v[46:47], 0, v[176:177]
	global_load_dwordx4 v[92:95], v[174:175], off offset:3584
	global_load_dwordx4 v[96:99], v[174:175], off offset:3648
	global_load_dwordx4 v[100:103], v[178:179], off offset:16
	global_load_dwordx4 v[104:107], v[178:179], off
	global_load_dwordx4 v[108:111], v[180:181], off offset:16
	global_load_dwordx4 v[112:115], v[180:181], off
	v_lshlrev_b32_e32 v71, 16, v4
	v_lshlrev_b32_e32 v70, 16, v8
	v_mov_b32_e32 v72, v66
	v_mov_b32_e32 v73, v16
	v_pk_mul_f32 v[72:73], v[72:73], v[70:71]
	s_nop 0
	v_sub_f32_e32 v1, v73, v72
	v_mov_b32_e32 v72, v16
	v_mov_b32_e32 v73, v66
	v_pk_mul_f32 v[70:71], v[72:73], v[70:71]
	v_mov_b32_e32 v66, v17
	v_add_f32_e32 v16, v70, v71
	v_mul_f32_e32 v51, 0x3e000000, v16
	v_and_b32_e32 v71, 0xffff0000, v4
	v_and_b32_e32 v70, 0xffff0000, v8
	v_mov_b32_e32 v16, v67
	v_pk_mul_f32 v[72:73], v[16:17], v[70:71]
	v_pk_mul_f32 v[16:17], v[66:67], v[70:71]
	v_sub_f32_e32 v4, v73, v72
	v_mul_f32_e32 v53, 0x3e000000, v4
	v_add_f32_e32 v4, v16, v17
	v_lshlrev_b32_e32 v17, 16, v5
	v_lshlrev_b32_e32 v16, 16, v9
	v_mov_b32_e32 v66, v68
	v_mov_b32_e32 v67, v18
	v_pk_mul_f32 v[66:67], v[66:67], v[16:17]
	v_mul_f32_e32 v55, 0x3e000000, v4
	v_sub_f32_e32 v4, v67, v66
	v_mov_b32_e32 v66, v18
	v_mov_b32_e32 v67, v68
	v_pk_mul_f32 v[16:17], v[66:67], v[16:17]
	v_mul_f32_e32 v57, 0x3e000000, v4
	v_add_f32_e32 v4, v16, v17
	v_mul_f32_e32 v16, 0x3e000000, v4
	v_and_b32_e32 v5, 0xffff0000, v5
	v_and_b32_e32 v4, 0xffff0000, v9
	v_mov_b32_e32 v18, v69
	v_mov_b32_e32 v68, v19
	v_pk_mul_f32 v[8:9], v[18:19], v[4:5]
	v_pk_mul_f32 v[4:5], v[68:69], v[4:5]
	v_sub_f32_e32 v8, v9, v8
	v_add_f32_e32 v4, v4, v5
	v_mul_f32_e32 v17, 0x3e000000, v8
	v_mul_f32_e32 v18, 0x3e000000, v4
	v_lshlrev_b32_e32 v5, 16, v6
	v_lshlrev_b32_e32 v4, 16, v10
	v_mov_b32_e32 v8, v20
	v_mov_b32_e32 v9, v12
	v_pk_mul_f32 v[8:9], v[8:9], v[4:5]
	v_mul_f32_e32 v1, 0x3e000000, v1
	v_sub_f32_e32 v8, v9, v8
	v_mul_f32_e32 v19, 0x3e000000, v8
	v_mov_b32_e32 v8, v12
	v_mov_b32_e32 v9, v20
	v_pk_mul_f32 v[4:5], v[8:9], v[4:5]
	v_mov_b32_e32 v12, v21
	v_add_f32_e32 v4, v4, v5
	v_mul_f32_e32 v59, 0x3e000000, v4
	v_and_b32_e32 v5, 0xffff0000, v6
	v_and_b32_e32 v4, 0xffff0000, v10
	v_mov_b32_e32 v20, v13
	v_pk_mul_f32 v[8:9], v[12:13], v[4:5]
	v_pk_mul_f32 v[4:5], v[20:21], v[4:5]
	v_sub_f32_e32 v6, v9, v8
	v_add_f32_e32 v4, v4, v5
	v_mul_f32_e32 v12, 0x3e000000, v4
	v_lshlrev_b32_e32 v5, 16, v7
	v_lshlrev_b32_e32 v4, 16, v11
	v_mov_b32_e32 v8, v22
	v_mov_b32_e32 v9, v14
	v_pk_mul_f32 v[8:9], v[8:9], v[4:5]
	v_mul_f32_e32 v10, 0x3e000000, v6
	v_sub_f32_e32 v6, v9, v8
	v_mov_b32_e32 v8, v14
	v_mov_b32_e32 v9, v22
	v_pk_mul_f32 v[4:5], v[8:9], v[4:5]
	v_mov_b32_e32 v14, v23
	v_add_f32_e32 v4, v4, v5
	v_mul_f32_e32 v8, 0x3e000000, v4
	v_and_b32_e32 v5, 0xffff0000, v7
	v_and_b32_e32 v4, 0xffff0000, v11
	v_mov_b32_e32 v22, v15
	v_mul_f32_e32 v13, 0x3e000000, v6
	v_pk_mul_f32 v[6:7], v[14:15], v[4:5]
	v_pk_mul_f32 v[4:5], v[22:23], v[4:5]
	v_sub_f32_e32 v6, v7, v6
	v_add_f32_e32 v4, v4, v5
	v_mul_f32_e32 v6, 0x3e000000, v6
	v_mul_f32_e32 v4, 0x3e000000, v4
	v_cvt_pk_bf16_f32 v1, v1, v53
	v_cvt_pk_bf16_f32 v5, v57, v17
	v_cvt_pk_bf16_f32 v6, v13, v6
	v_cvt_pk_bf16_f32 v9, v51, v55
	v_cvt_pk_bf16_f32 v4, v8, v4
	v_cvt_pk_bf16_f32 v7, v19, v10
	v_cvt_pk_bf16_f32 v10, v16, v18
	v_cvt_pk_bf16_f32 v11, v59, v12
	v_add_u32_e32 v12, -16, v0
	v_cndmask_b32_e32 v1, v9, v1, vcc
	v_cndmask_b32_e32 v4, v4, v6, vcc
	v_cndmask_b32_e32 v6, v11, v7, vcc
	v_cndmask_b32_e32 v5, v10, v5, vcc
	ds_write_b16 v29, v1 offset:64
	ds_write_b16_d16_hi v29, v1 offset:208
	ds_write_b16 v29, v5 offset:352
	ds_write_b16_d16_hi v29, v5 offset:496
	ds_write_b16 v29, v6 offset:640
	ds_write_b16_d16_hi v29, v6 offset:784
	ds_write_b16 v29, v4 offset:928
	ds_write_b16_d16_hi v29, v4 offset:1072
	v_or_b32_e32 v1, s20, v36
	v_mad_u64_u32 v[4:5], s[0:1], v1, s5, v[2:3]
	v_mad_i32_i24 v5, s17, v207, v5
	v_ashrrev_i32_e32 v13, 31, v12
	v_lshl_add_u64 v[4:5], v[4:5], 0, s[38:39]
	v_lshlrev_b64 v[12:13], 7, v[12:13]
	v_lshl_add_u64 v[8:9], v[4:5], 0, v[60:61]
	v_lshl_add_u64 v[16:17], v[44:45], 0, v[12:13]
	v_lshl_add_u64 v[66:67], v[46:47], 0, v[12:13]
	s_nop 0
	s_nop 0
	s_nop 0
	s_nop 0
	s_nop 0
	s_waitcnt vmcnt(6)
; #define LAS __attribute__((address_space(3)))
; __device__ __forceinline__ void retkv_item(const bf16_t* hbuf, const float* rot, float* kvbuf, LAS bf16_t* wl, int item, int lane) {
;     ...
;     { const int cr = lane >> 3, dc = lane & 7, fc = dc & 3;
; #pragma unroll
;       for (int i = 0; i < 8; ++i) { const int row = cr + 8 * i; const bf16_t* kp = hbuf + (t0 + row) * INWP + C_RK + h * 64;
;           const u32x4 x1 = *(const u32x4*)(kp + 8 * fc), x2 = *(const u32x4*)(kp + 32 + 8 * fc);
;           const int pos = n * 64 + row; u32x4 o1, o2;
;           rot8(x1, x2, rot + (size_t)pos * 32 + 8 * fc, rot + 16384 * 32 + (size_t)pos * 32 + 8 * fc, 0.125f, o1, o2);
;           const u32x4 w = dc < 4 ? o1 : o2;
;           LAS bf16_t* t = kT + (8 * dc) * TLD + row;
;           t[0 * TLD] = (bf16_t)(w.x & 0xffff); t[1 * TLD] = (bf16_t)(w.x >> 16); t[2 * TLD] = (bf16_t)(w.y & 0xffff); t[3 * TLD] = (bf16_t)(w.y >> 16);
;           t[4 * TLD] = (bf16_t)(w.z & 0xffff); t[5 * TLD] = (bf16_t)(w.z >> 16); t[6 * TLD] = (bf16_t)(w.w & 0xffff); t[7 * TLD] = (bf16_t)(w.w >> 16); } }
	v_mov_b32_e32 v4, v140
	v_mov_b32_e32 v5, v141
	v_mov_b32_e32 v6, v142
	v_mov_b32_e32 v7, v143
	v_mov_b32_e32 v8, v144
	v_mov_b32_e32 v9, v145
	v_mov_b32_e32 v10, v146
	v_mov_b32_e32 v11, v147
	v_mov_b32_e32 v12, v148
	v_mov_b32_e32 v13, v149
	v_mov_b32_e32 v14, v150
	v_mov_b32_e32 v15, v151
	v_mov_b32_e32 v16, v152
	v_mov_b32_e32 v17, v153
	v_mov_b32_e32 v18, v154
	v_mov_b32_e32 v19, v155
	v_mov_b32_e32 v20, v156
	v_mov_b32_e32 v21, v157
	v_mov_b32_e32 v22, v158
	v_mov_b32_e32 v23, v159
	v_mov_b32_e32 v66, v160
	v_mov_b32_e32 v67, v161
	v_mov_b32_e32 v68, v162
	v_mov_b32_e32 v69, v163
	v_or_b32_e32 v172, s20, v42
	v_mad_u64_u32 v[174:175], s[100:101], v172, s5, v[2:3]
	v_mad_i32_i24 v175, s17, v207, v175
	v_lshl_add_u64 v[174:175], v[174:175], 0, s[38:39]
	v_lshl_add_u64 v[174:175], v[174:175], 0, v[60:61]
	v_mov_b32_e32 v176, v0
	v_ashrrev_i32_e32 v177, 31, v176
	v_lshlrev_b64 v[176:177], 7, v[176:177]
	v_lshl_add_u64 v[178:179], v[44:45], 0, v[176:177]
	v_lshl_add_u64 v[180:181], v[46:47], 0, v[176:177]
	global_load_dwordx4 v[116:119], v[174:175], off offset:3584
	global_load_dwordx4 v[120:123], v[174:175], off offset:3648
	global_load_dwordx4 v[124:127], v[178:179], off offset:16
	global_load_dwordx4 v[128:131], v[178:179], off
	global_load_dwordx4 v[132:135], v[180:181], off offset:16
	global_load_dwordx4 v[136:139], v[180:181], off
	v_lshlrev_b32_e32 v71, 16, v4
	v_lshlrev_b32_e32 v70, 16, v8
	v_mov_b32_e32 v72, v66
	v_mov_b32_e32 v73, v16
	v_pk_mul_f32 v[72:73], v[72:73], v[70:71]
	s_nop 0
	v_sub_f32_e32 v1, v73, v72
	v_mov_b32_e32 v72, v16
	v_mov_b32_e32 v73, v66
	v_pk_mul_f32 v[70:71], v[72:73], v[70:71]
	v_mov_b32_e32 v66, v17
	v_add_f32_e32 v16, v70, v71
	v_mul_f32_e32 v51, 0x3e000000, v16
	v_and_b32_e32 v71, 0xffff0000, v4
	v_and_b32_e32 v70, 0xffff0000, v8
	v_mov_b32_e32 v16, v67
	v_pk_mul_f32 v[72:73], v[16:17], v[70:71]
	v_pk_mul_f32 v[16:17], v[66:67], v[70:71]
	v_sub_f32_e32 v4, v73, v72
	v_mul_f32_e32 v53, 0x3e000000, v4
	v_add_f32_e32 v4, v16, v17
	v_lshlrev_b32_e32 v17, 16, v5
	v_lshlrev_b32_e32 v16, 16, v9
	v_mov_b32_e32 v66, v68
	v_mov_b32_e32 v67, v18
	v_pk_mul_f32 v[66:67], v[66:67], v[16:17]
	v_mul_f32_e32 v55, 0x3e000000, v4
	v_sub_f32_e32 v4, v67, v66
	v_mov_b32_e32 v66, v18
	v_mov_b32_e32 v67, v68
	v_pk_mul_f32 v[16:17], v[66:67], v[16:17]
	v_mul_f32_e32 v57, 0x3e000000, v4
	v_add_f32_e32 v4, v16, v17
	v_mul_f32_e32 v16, 0x3e000000, v4
	v_and_b32_e32 v5, 0xffff0000, v5
	v_and_b32_e32 v4, 0xffff0000, v9
	v_mov_b32_e32 v18, v69
	v_mov_b32_e32 v68, v19
	v_pk_mul_f32 v[8:9], v[18:19], v[4:5]
	v_pk_mul_f32 v[4:5], v[68:69], v[4:5]
	v_sub_f32_e32 v8, v9, v8
	v_add_f32_e32 v4, v4, v5
	v_mul_f32_e32 v17, 0x3e000000, v8
	v_mul_f32_e32 v18, 0x3e000000, v4
	v_lshlrev_b32_e32 v5, 16, v6
	v_lshlrev_b32_e32 v4, 16, v10
	v_mov_b32_e32 v8, v20
	v_mov_b32_e32 v9, v12
	v_pk_mul_f32 v[8:9], v[8:9], v[4:5]
	v_mul_f32_e32 v1, 0x3e000000, v1
	v_sub_f32_e32 v8, v9, v8
	v_mul_f32_e32 v19, 0x3e000000, v8
	v_mov_b32_e32 v8, v12
	v_mov_b32_e32 v9, v20
	v_pk_mul_f32 v[4:5], v[8:9], v[4:5]
	v_mov_b32_e32 v12, v21
	v_add_f32_e32 v4, v4, v5
	v_mul_f32_e32 v59, 0x3e000000, v4
	v_and_b32_e32 v5, 0xffff0000, v6
	v_and_b32_e32 v4, 0xffff0000, v10
	v_mov_b32_e32 v20, v13
	v_pk_mul_f32 v[8:9], v[12:13], v[4:5]
	v_pk_mul_f32 v[4:5], v[20:21], v[4:5]
	v_sub_f32_e32 v6, v9, v8
	v_add_f32_e32 v4, v4, v5
	v_mul_f32_e32 v12, 0x3e000000, v4
	v_lshlrev_b32_e32 v5, 16, v7
	v_lshlrev_b32_e32 v4, 16, v11
	v_mov_b32_e32 v8, v22
	v_mov_b32_e32 v9, v14
	v_pk_mul_f32 v[8:9], v[8:9], v[4:5]
	v_mul_f32_e32 v10, 0x3e000000, v6
	v_sub_f32_e32 v6, v9, v8
	v_mov_b32_e32 v8, v14
	v_mov_b32_e32 v9, v22
	v_pk_mul_f32 v[4:5], v[8:9], v[4:5]
	v_mov_b32_e32 v14, v23
	v_add_f32_e32 v4, v4, v5
	v_mul_f32_e32 v8, 0x3e000000, v4
	v_and_b32_e32 v5, 0xffff0000, v7
	v_and_b32_e32 v4, 0xffff0000, v11
	v_mov_b32_e32 v22, v15
	v_mul_f32_e32 v13, 0x3e000000, v6
	v_pk_mul_f32 v[6:7], v[14:15], v[4:5]
	v_pk_mul_f32 v[4:5], v[22:23], v[4:5]
	v_sub_f32_e32 v6, v7, v6
	v_add_f32_e32 v4, v4, v5
	v_mul_f32_e32 v6, 0x3e000000, v6
	v_mul_f32_e32 v4, 0x3e000000, v4
	v_cvt_pk_bf16_f32 v1, v1, v53
	v_cvt_pk_bf16_f32 v5, v57, v17
	v_cvt_pk_bf16_f32 v6, v13, v6
	v_cvt_pk_bf16_f32 v9, v51, v55
	v_cvt_pk_bf16_f32 v4, v8, v4
	v_cvt_pk_bf16_f32 v7, v19, v10
	v_cvt_pk_bf16_f32 v10, v16, v18
	v_cvt_pk_bf16_f32 v11, v59, v12
	v_add_u32_e32 v12, -8, v0
	v_cndmask_b32_e32 v1, v9, v1, vcc
	v_cndmask_b32_e32 v4, v4, v6, vcc
	v_cndmask_b32_e32 v6, v11, v7, vcc
	v_cndmask_b32_e32 v5, v10, v5, vcc
	ds_write_b16 v29, v1 offset:80
	ds_write_b16_d16_hi v29, v1 offset:224
	ds_write_b16 v29, v5 offset:368
	ds_write_b16_d16_hi v29, v5 offset:512
	ds_write_b16 v29, v6 offset:656
	ds_write_b16_d16_hi v29, v6 offset:800
	ds_write_b16 v29, v4 offset:944
	ds_write_b16_d16_hi v29, v4 offset:1088
	v_or_b32_e32 v1, s20, v40
	v_mad_u64_u32 v[4:5], s[0:1], v1, s5, v[2:3]
	v_mad_i32_i24 v5, s17, v207, v5
	v_ashrrev_i32_e32 v13, 31, v12
	v_lshl_add_u64 v[4:5], v[4:5], 0, s[38:39]
	v_lshlrev_b64 v[12:13], 7, v[12:13]
	v_lshl_add_u64 v[8:9], v[4:5], 0, v[60:61]
	v_lshl_add_u64 v[16:17], v[44:45], 0, v[12:13]
	v_lshl_add_u64 v[66:67], v[46:47], 0, v[12:13]
	s_nop 0
	s_nop 0
	s_nop 0
	s_nop 0
	s_nop 0
	s_waitcnt vmcnt(6)
; #define LAS __attribute__((address_space(3)))
; __device__ __forceinline__ void retkv_item(const bf16_t* hbuf, const float* rot, float* kvbuf, LAS bf16_t* wl, int item, int lane) {
;     ...
;     { const int cr = lane >> 3, dc = lane & 7, fc = dc & 3;
; #pragma unroll
;       for (int i = 0; i < 8; ++i) { const int row = cr + 8 * i; const bf16_t* kp = hbuf + (t0 + row) * INWP + C_RK + h * 64;
;           const u32x4 x1 = *(const u32x4*)(kp + 8 * fc), x2 = *(const u32x4*)(kp + 32 + 8 * fc);
;           const int pos = n * 64 + row; u32x4 o1, o2;
;           rot8(x1, x2, rot + (size_t)pos * 32 + 8 * fc, rot + 16384 * 32 + (size_t)pos * 32 + 8 * fc, 0.125f, o1, o2);
;           const u32x4 w = dc < 4 ? o1 : o2;
;           LAS bf16_t* t = kT + (8 * dc) * TLD + row;
;           t[0 * TLD] = (bf16_t)(w.x & 0xffff); t[1 * TLD] = (bf16_t)(w.x >> 16); t[2 * TLD] = (bf16_t)(w.y & 0xffff); t[3 * TLD] = (bf16_t)(w.y >> 16);
;           t[4 * TLD] = (bf16_t)(w.z & 0xffff); t[5 * TLD] = (bf16_t)(w.z >> 16); t[6 * TLD] = (bf16_t)(w.w & 0xffff); t[7 * TLD] = (bf16_t)(w.w >> 16); } }
	v_mov_b32_e32 v4, v92
	v_mov_b32_e32 v5, v93
	v_mov_b32_e32 v6, v94
	v_mov_b32_e32 v7, v95
	v_mov_b32_e32 v8, v96
	v_mov_b32_e32 v9, v97
	v_mov_b32_e32 v10, v98
	v_mov_b32_e32 v11, v99
	v_mov_b32_e32 v12, v100
	v_mov_b32_e32 v13, v101
	v_mov_b32_e32 v14, v102
	v_mov_b32_e32 v15, v103
	v_mov_b32_e32 v16, v104
	v_mov_b32_e32 v17, v105
	v_mov_b32_e32 v18, v106
	v_mov_b32_e32 v19, v107
	v_mov_b32_e32 v20, v108
	v_mov_b32_e32 v21, v109
	v_mov_b32_e32 v22, v110
	v_mov_b32_e32 v23, v111
	v_mov_b32_e32 v66, v112
	v_mov_b32_e32 v67, v113
	v_mov_b32_e32 v68, v114
	v_mov_b32_e32 v69, v115
	v_lshlrev_b32_e32 v71, 16, v4
	v_lshlrev_b32_e32 v70, 16, v8
	v_mov_b32_e32 v72, v66
	v_mov_b32_e32 v73, v16
	v_pk_mul_f32 v[72:73], v[72:73], v[70:71]
	s_nop 0
	v_sub_f32_e32 v1, v73, v72
	v_mov_b32_e32 v72, v16
	v_mov_b32_e32 v73, v66
	v_pk_mul_f32 v[70:71], v[72:73], v[70:71]
	v_mov_b32_e32 v66, v17
	v_add_f32_e32 v16, v70, v71
	v_mul_f32_e32 v51, 0x3e000000, v16
	v_and_b32_e32 v71, 0xffff0000, v4
	v_and_b32_e32 v70, 0xffff0000, v8
	v_mov_b32_e32 v16, v67
	v_pk_mul_f32 v[72:73], v[16:17], v[70:71]
	v_pk_mul_f32 v[16:17], v[66:67], v[70:71]
	v_sub_f32_e32 v4, v73, v72
	v_mul_f32_e32 v53, 0x3e000000, v4
	v_add_f32_e32 v4, v16, v17
	v_lshlrev_b32_e32 v17, 16, v5
	v_lshlrev_b32_e32 v16, 16, v9
	v_mov_b32_e32 v66, v68
	v_mov_b32_e32 v67, v18
	v_pk_mul_f32 v[66:67], v[66:67], v[16:17]
	v_mul_f32_e32 v55, 0x3e000000, v4
	v_sub_f32_e32 v4, v67, v66
	v_mov_b32_e32 v66, v18
	v_mov_b32_e32 v67, v68
	v_pk_mul_f32 v[16:17], v[66:67], v[16:17]
	v_mul_f32_e32 v57, 0x3e000000, v4
	v_add_f32_e32 v4, v16, v17
	v_mul_f32_e32 v16, 0x3e000000, v4
	v_and_b32_e32 v5, 0xffff0000, v5
	v_and_b32_e32 v4, 0xffff0000, v9
	v_mov_b32_e32 v18, v69
	v_mov_b32_e32 v68, v19
	v_pk_mul_f32 v[8:9], v[18:19], v[4:5]
	v_pk_mul_f32 v[4:5], v[68:69], v[4:5]
	v_sub_f32_e32 v8, v9, v8
	v_add_f32_e32 v4, v4, v5
	v_mul_f32_e32 v17, 0x3e000000, v8
	v_mul_f32_e32 v18, 0x3e000000, v4
	v_lshlrev_b32_e32 v5, 16, v6
	v_lshlrev_b32_e32 v4, 16, v10
	v_mov_b32_e32 v8, v20
	v_mov_b32_e32 v9, v12
	v_pk_mul_f32 v[8:9], v[8:9], v[4:5]
	v_mul_f32_e32 v1, 0x3e000000, v1
	v_sub_f32_e32 v8, v9, v8
	v_mul_f32_e32 v19, 0x3e000000, v8
	v_mov_b32_e32 v8, v12
	v_mov_b32_e32 v9, v20
	v_pk_mul_f32 v[4:5], v[8:9], v[4:5]
	v_mov_b32_e32 v12, v21
	v_add_f32_e32 v4, v4, v5
	v_mul_f32_e32 v59, 0x3e000000, v4
	v_and_b32_e32 v5, 0xffff0000, v6
	v_and_b32_e32 v4, 0xffff0000, v10
	v_mov_b32_e32 v20, v13
	v_pk_mul_f32 v[8:9], v[12:13], v[4:5]
	v_pk_mul_f32 v[4:5], v[20:21], v[4:5]
	v_sub_f32_e32 v6, v9, v8
	v_add_f32_e32 v4, v4, v5
	v_mul_f32_e32 v12, 0x3e000000, v4
	v_lshlrev_b32_e32 v5, 16, v7
	v_lshlrev_b32_e32 v4, 16, v11
	v_mov_b32_e32 v8, v22
	v_mov_b32_e32 v9, v14
	v_pk_mul_f32 v[8:9], v[8:9], v[4:5]
	v_mul_f32_e32 v10, 0x3e000000, v6
	v_sub_f32_e32 v6, v9, v8
	v_mov_b32_e32 v8, v14
	v_mov_b32_e32 v9, v22
	v_pk_mul_f32 v[4:5], v[8:9], v[4:5]
	v_mov_b32_e32 v14, v23
	v_add_f32_e32 v4, v4, v5
	v_mul_f32_e32 v8, 0x3e000000, v4
	v_and_b32_e32 v5, 0xffff0000, v7
	v_and_b32_e32 v4, 0xffff0000, v11
	v_mov_b32_e32 v22, v15
	v_mul_f32_e32 v13, 0x3e000000, v6
	v_pk_mul_f32 v[6:7], v[14:15], v[4:5]
	v_pk_mul_f32 v[4:5], v[22:23], v[4:5]
	v_sub_f32_e32 v6, v7, v6
	v_add_f32_e32 v4, v4, v5
	v_mul_f32_e32 v6, 0x3e000000, v6
	v_mul_f32_e32 v4, 0x3e000000, v4
	v_cvt_pk_bf16_f32 v1, v1, v53
	v_cvt_pk_bf16_f32 v5, v57, v17
	v_cvt_pk_bf16_f32 v6, v13, v6
	v_cvt_pk_bf16_f32 v9, v51, v55
	v_cvt_pk_bf16_f32 v4, v8, v4
	v_cvt_pk_bf16_f32 v7, v19, v10
	v_cvt_pk_bf16_f32 v10, v16, v18
	v_cvt_pk_bf16_f32 v11, v59, v12
	s_nop 0
	v_cndmask_b32_e32 v1, v9, v1, vcc
	v_cndmask_b32_e32 v4, v4, v6, vcc
	v_cndmask_b32_e32 v6, v11, v7, vcc
	v_cndmask_b32_e32 v5, v10, v5, vcc
	ds_write_b16 v29, v1 offset:96
	ds_write_b16_d16_hi v29, v1 offset:240
	ds_write_b16 v29, v5 offset:384
	ds_write_b16_d16_hi v29, v5 offset:528
	ds_write_b16 v29, v6 offset:672
	ds_write_b16_d16_hi v29, v6 offset:816
	ds_write_b16 v29, v4 offset:960
	ds_write_b16_d16_hi v29, v4 offset:1104
	v_or_b32_e32 v1, s20, v42
	v_mad_u64_u32 v[2:3], s[0:1], v1, s5, v[2:3]
	v_mad_i32_i24 v3, s17, v207, v3
	v_lshl_add_u64 v[2:3], v[2:3], 0, s[38:39]
	v_ashrrev_i32_e32 v1, 31, v0
	v_lshl_add_u64 v[2:3], v[2:3], 0, v[60:61]
	v_lshlrev_b64 v[0:1], 7, v[0:1]
	v_lshl_add_u64 v[2:3], v[44:45], 0, v[0:1]
	v_lshl_add_u64 v[20:21], v[46:47], 0, v[0:1]
	s_nop 0
	s_nop 0
	s_waitcnt vmcnt(0)
; #define LAS __attribute__((address_space(3)))
; __device__ __forceinline__ void retkv_item(const bf16_t* hbuf, const float* rot, float* kvbuf, LAS bf16_t* wl, int item, int lane) {
;     ...
;     { const int cr = lane >> 3, dc = lane & 7, fc = dc & 3;
; #pragma unroll
;       for (int i = 0; i < 8; ++i) { const int row = cr + 8 * i; const bf16_t* kp = hbuf + (t0 + row) * INWP + C_RK + h * 64;
;           const u32x4 x1 = *(const u32x4*)(kp + 8 * fc), x2 = *(const u32x4*)(kp + 32 + 8 * fc);
;           const int pos = n * 64 + row; u32x4 o1, o2;
;           rot8(x1, x2, rot + (size_t)pos * 32 + 8 * fc, rot + 16384 * 32 + (size_t)pos * 32 + 8 * fc, 0.125f, o1, o2);
;           const u32x4 w = dc < 4 ? o1 : o2;
;           LAS bf16_t* t = kT + (8 * dc) * TLD + row;
;           t[0 * TLD] = (bf16_t)(w.x & 0xffff); t[1 * TLD] = (bf16_t)(w.x >> 16); t[2 * TLD] = (bf16_t)(w.y & 0xffff); t[3 * TLD] = (bf16_t)(w.y >> 16);
;           t[4 * TLD] = (bf16_t)(w.z & 0xffff); t[5 * TLD] = (bf16_t)(w.z >> 16); t[6 * TLD] = (bf16_t)(w.w & 0xffff); t[7 * TLD] = (bf16_t)(w.w >> 16); } }
	v_mov_b32_e32 v8, v116
	v_mov_b32_e32 v9, v117
	v_mov_b32_e32 v10, v118
	v_mov_b32_e32 v11, v119
	v_mov_b32_e32 v12, v120
	v_mov_b32_e32 v13, v121
	v_mov_b32_e32 v14, v122
	v_mov_b32_e32 v15, v123
	v_mov_b32_e32 v4, v124
	v_mov_b32_e32 v5, v125
	v_mov_b32_e32 v6, v126
	v_mov_b32_e32 v7, v127
	v_mov_b32_e32 v16, v128
	v_mov_b32_e32 v17, v129
	v_mov_b32_e32 v18, v130
	v_mov_b32_e32 v19, v131
	v_mov_b32_e32 v0, v132
	v_mov_b32_e32 v1, v133
	v_mov_b32_e32 v2, v134
	v_mov_b32_e32 v3, v135
	v_mov_b32_e32 v20, v136
	v_mov_b32_e32 v21, v137
	v_mov_b32_e32 v22, v138
	v_mov_b32_e32 v23, v139
	s_lshl_b64 s[0:1], s[36:37], 14
	v_lshl_add_u64 v[86:87], v[48:49], 0, s[0:1]
	v_add_co_u32_e64 v88, s[0:1], s45, v86
	s_add_i32 s36, s36, s14
	s_nop 0
	v_addc_co_u32_e64 v89, s[0:1], 0, v87, s[0:1]
	v_add_co_u32_e64 v90, s[0:1], s27, v86
	s_cmpk_gt_i32 s36, 0xbff
	s_nop 0
	v_addc_co_u32_e64 v91, s[0:1], 0, v87, s[0:1]
	v_lshlrev_b32_e32 v67, 16, v8
	v_lshlrev_b32_e32 v66, 16, v12
	v_mov_b32_e32 v69, v16
	v_mov_b32_e32 v68, v20
	v_pk_mul_f32 v[68:69], v[68:69], v[66:67]
	s_nop 0
	v_sub_f32_e32 v51, v69, v68
	v_mov_b32_e32 v68, v16
	v_mov_b32_e32 v69, v20
	v_pk_mul_f32 v[66:67], v[68:69], v[66:67]
	v_mov_b32_e32 v20, v17
	v_add_f32_e32 v16, v66, v67
	v_mul_f32_e32 v53, 0x3e000000, v16
	v_and_b32_e32 v67, 0xffff0000, v8
	v_and_b32_e32 v66, 0xffff0000, v12
	v_mov_b32_e32 v16, v21
	v_pk_mul_f32 v[68:69], v[16:17], v[66:67]
	v_pk_mul_f32 v[16:17], v[20:21], v[66:67]
	v_lshlrev_b32_e32 v21, 16, v9
	v_add_f32_e32 v12, v16, v17
	v_lshlrev_b32_e32 v20, 16, v13
	v_mov_b32_e32 v16, v22
	v_mov_b32_e32 v17, v18
	v_mov_b32_e32 v66, v18
	v_mov_b32_e32 v67, v22
	v_pk_mul_f32 v[16:17], v[16:17], v[20:21]
	v_pk_mul_f32 v[20:21], v[66:67], v[20:21]
	v_sub_f32_e32 v16, v17, v16
	v_add_f32_e32 v17, v20, v21
	v_and_b32_e32 v21, 0xffff0000, v9
	v_and_b32_e32 v20, 0xffff0000, v13
	v_mov_b32_e32 v18, v23
	v_mov_b32_e32 v22, v19
	v_pk_mul_f32 v[66:67], v[18:19], v[20:21]
	v_pk_mul_f32 v[18:19], v[22:23], v[20:21]
	v_lshlrev_b32_e32 v21, 16, v10
	v_add_f32_e32 v13, v18, v19
	v_lshlrev_b32_e32 v20, 16, v14
	v_mov_b32_e32 v18, v0
	v_mov_b32_e32 v19, v4
	v_mov_b32_e32 v22, v4
	v_mov_b32_e32 v23, v0
	v_pk_mul_f32 v[18:19], v[18:19], v[20:21]
	v_pk_mul_f32 v[20:21], v[22:23], v[20:21]
	v_mov_b32_e32 v4, v1
	v_add_f32_e32 v0, v20, v21
	v_and_b32_e32 v21, 0xffff0000, v10
	v_and_b32_e32 v20, 0xffff0000, v14
	v_pk_mul_f32 v[22:23], v[4:5], v[20:21]
	v_sub_f32_e32 v18, v19, v18
	v_mul_f32_e32 v19, 0x3e000000, v0
	v_sub_f32_e32 v0, v23, v22
	v_mul_f32_e32 v4, 0x3e000000, v0
	v_mov_b32_e32 v0, v5
	v_pk_mul_f32 v[0:1], v[0:1], v[20:21]
	v_mov_b32_e32 v20, v2
	v_add_f32_e32 v0, v0, v1
	v_mul_f32_e32 v5, 0x3e000000, v0
	v_lshlrev_b32_e32 v1, 16, v11
	v_lshlrev_b32_e32 v0, 16, v15
	v_mov_b32_e32 v21, v6
	v_pk_mul_f32 v[20:21], v[20:21], v[0:1]
	v_sub_f32_e32 v8, v69, v68
	v_sub_f32_e32 v10, v21, v20
	v_mov_b32_e32 v20, v6
	v_mov_b32_e32 v21, v2
	v_pk_mul_f32 v[0:1], v[20:21], v[0:1]
	v_mov_b32_e32 v6, v3
	v_add_f32_e32 v0, v0, v1
	v_mul_f32_e32 v14, 0x3e000000, v0
	v_and_b32_e32 v1, 0xffff0000, v11
	v_and_b32_e32 v0, 0xffff0000, v15
	v_pk_mul_f32 v[20:21], v[6:7], v[0:1]
	v_mul_f32_e32 v51, 0x3e000000, v51
	v_sub_f32_e32 v2, v21, v20
	v_mul_f32_e32 v6, 0x3e000000, v2
	v_mov_b32_e32 v2, v7
	v_pk_mul_f32 v[0:1], v[2:3], v[0:1]
	v_mul_f32_e32 v8, 0x3e000000, v8
	v_add_f32_e32 v0, v0, v1
	v_sub_f32_e32 v9, v67, v66
	v_mul_f32_e32 v0, 0x3e000000, v0
	v_cvt_pk_bf16_f32 v1, v51, v8
	v_mul_f32_e32 v12, 0x3e000000, v12
	v_mul_f32_e32 v16, 0x3e000000, v16
	v_mul_f32_e32 v9, 0x3e000000, v9
	v_mul_f32_e32 v18, 0x3e000000, v18
	v_mul_f32_e32 v10, 0x3e000000, v10
	v_cvt_pk_bf16_f32 v2, v16, v9
	v_cvt_pk_bf16_f32 v3, v18, v4
	v_cvt_pk_bf16_f32 v4, v10, v6
	v_cvt_pk_bf16_f32 v6, v53, v12
	v_cvt_pk_bf16_f32 v0, v14, v0
	v_mul_f32_e32 v17, 0x3e000000, v17
	v_cndmask_b32_e32 v1, v6, v1, vcc
	v_mul_f32_e32 v13, 0x3e000000, v13
	v_cvt_pk_bf16_f32 v7, v17, v13
	v_cvt_pk_bf16_f32 v5, v19, v5
	v_cndmask_b32_e32 v0, v0, v4, vcc
	v_cndmask_b32_e32 v3, v5, v3, vcc
	v_cndmask_b32_e32 v2, v7, v2, vcc
	ds_write_b16 v29, v1 offset:112
	ds_write_b16_d16_hi v29, v1 offset:256
	ds_write_b16 v29, v2 offset:400
	ds_write_b16_d16_hi v29, v2 offset:544
	ds_write_b16 v29, v3 offset:688
	ds_write_b16_d16_hi v29, v3 offset:832
	ds_write_b16 v29, v0 offset:976
	ds_write_b16_d16_hi v29, v0 offset:1120
	s_waitcnt lgkmcnt(0)
; #define LAS __attribute__((address_space(3)))
; __device__ __forceinline__ void retkv_item(const bf16_t* hbuf, const float* rot, float* kvbuf, LAS bf16_t* wl, int item, int lane) {
;     ...
;     const int r = lane & 15, q = lane >> 4;
;     float* outp = kvbuf + (size_t)item * 4096;
; #pragma unroll
;     for (int et = 0; et < 4; ++et) {
;         bf16x8 vf[2];
; #pragma unroll
;         for (int ks = 0; ks < 2; ++ks) vf[ks] = *(const LAS bf16x8*)(vT + (16 * et + r) * TLD + 32 * ks + 8 * q);
; #pragma unroll
;         for (int dt = 0; dt < 4; ++dt) { f32x4 acc = {0.f, 0.f, 0.f, 0.f};
; #pragma unroll
;             for (int ks = 0; ks < 2; ++ks) { const bf16x8 kf = *(const LAS bf16x8*)(kT + (16 * dt + r) * TLD + 32 * ks + 8 * q);
;                 acc = __builtin_amdgcn_mfma_f32_16x16x32_bf16(kf, vf[ks], acc, 0, 0, 0); }
;             *(f32x4*)(outp + (16 * et + r) * 64 + 16 * dt + 4 * q) = acc; } }
	ds_read_b128 v[0:3], v64 offset:9216
	ds_read_b128 v[4:7], v64 offset:9280
	ds_read_b128 v[8:11], v64
	ds_read_b128 v[16:19], v64 offset:64
	s_waitcnt lgkmcnt(1)
	v_mfma_f32_16x16x32_bf16 v[12:15], v[8:11], v[0:3], 0
	ds_read_b128 v[66:69], v64 offset:2368
	ds_read_b128 v[74:77], v64 offset:4672
	s_waitcnt lgkmcnt(2)
	v_mfma_f32_16x16x32_bf16 v[12:15], v[16:19], v[4:7], v[12:15]
	s_nop 7
	global_store_dwordx4 v[86:87], v[12:15], off
	ds_read_b128 v[12:15], v64 offset:2304
	s_waitcnt lgkmcnt(0)
	v_mfma_f32_16x16x32_bf16 v[20:23], v[12:15], v[0:3], 0
	v_mfma_f32_16x16x32_bf16 v[20:23], v[66:69], v[4:7], v[20:23]
	s_nop 7
	global_store_dwordx4 v[86:87], v[20:23], off offset:64
	ds_read_b128 v[20:23], v64 offset:4608
	s_waitcnt lgkmcnt(0)
	v_mfma_f32_16x16x32_bf16 v[70:73], v[20:23], v[0:3], 0
	v_mfma_f32_16x16x32_bf16 v[70:73], v[74:77], v[4:7], v[70:73]
	s_nop 7
	global_store_dwordx4 v[86:87], v[70:73], off offset:128
	ds_read_b128 v[70:73], v65
	s_waitcnt lgkmcnt(0)
	v_mfma_f32_16x16x32_bf16 v[78:81], v[70:73], v[0:3], 0
	ds_read_b128 v[0:3], v65 offset:64
	s_waitcnt lgkmcnt(0)
	v_mfma_f32_16x16x32_bf16 v[4:7], v[0:3], v[4:7], v[78:81]
	s_nop 7
	global_store_dwordx4 v[86:87], v[4:7], off offset:192
	ds_read_b128 v[4:7], v64 offset:11520
	ds_read_b128 v[78:81], v64 offset:11584
	s_waitcnt lgkmcnt(1)
	v_mfma_f32_16x16x32_bf16 v[82:85], v[8:11], v[4:7], 0
	s_waitcnt lgkmcnt(0)
	v_mfma_f32_16x16x32_bf16 v[82:85], v[16:19], v[78:81], v[82:85]
	s_nop 7
	global_store_dwordx4 v[90:91], v[82:85], off offset:-4096
	s_nop 1
	v_mfma_f32_16x16x32_bf16 v[82:85], v[12:15], v[4:7], 0
	v_mfma_f32_16x16x32_bf16 v[82:85], v[66:69], v[78:81], v[82:85]
	s_nop 7
	global_store_dwordx4 v[88:89], v[82:85], off offset:64
	s_nop 1
	v_mfma_f32_16x16x32_bf16 v[82:85], v[20:23], v[4:7], 0
	v_mfma_f32_16x16x32_bf16 v[4:7], v[70:73], v[4:7], 0
	v_mfma_f32_16x16x32_bf16 v[82:85], v[74:77], v[78:81], v[82:85]
	v_mfma_f32_16x16x32_bf16 v[4:7], v[0:3], v[78:81], v[4:7]
	s_nop 6
	global_store_dwordx4 v[88:89], v[82:85], off offset:128
	global_store_dwordx4 v[88:89], v[4:7], off offset:192
	ds_read_b128 v[4:7], v64 offset:13824
	ds_read_b128 v[78:81], v64 offset:13888
	s_waitcnt lgkmcnt(1)
	v_mfma_f32_16x16x32_bf16 v[82:85], v[8:11], v[4:7], 0
	s_waitcnt lgkmcnt(0)
	v_mfma_f32_16x16x32_bf16 v[82:85], v[16:19], v[78:81], v[82:85]
	s_nop 7
	global_store_dwordx4 v[90:91], v[82:85], off
	s_nop 1
	v_mfma_f32_16x16x32_bf16 v[82:85], v[12:15], v[4:7], 0
	v_mfma_f32_16x16x32_bf16 v[82:85], v[66:69], v[78:81], v[82:85]
	s_nop 7
	global_store_dwordx4 v[90:91], v[82:85], off offset:64
	s_nop 1
	v_mfma_f32_16x16x32_bf16 v[82:85], v[20:23], v[4:7], 0
	v_mfma_f32_16x16x32_bf16 v[4:7], v[70:73], v[4:7], 0
	v_mfma_f32_16x16x32_bf16 v[82:85], v[74:77], v[78:81], v[82:85]
	v_mfma_f32_16x16x32_bf16 v[4:7], v[0:3], v[78:81], v[4:7]
	s_nop 6
	global_store_dwordx4 v[90:91], v[82:85], off offset:128
	global_store_dwordx4 v[90:91], v[4:7], off offset:192
	ds_read_b128 v[4:7], v65 offset:9216
	ds_read_b128 v[78:81], v65 offset:9280
	s_waitcnt lgkmcnt(1)
	v_mfma_f32_16x16x32_bf16 v[8:11], v[8:11], v[4:7], 0
	s_waitcnt lgkmcnt(0)
	v_mfma_f32_16x16x32_bf16 v[8:11], v[16:19], v[78:81], v[8:11]
	v_add_co_u32_e64 v16, s[0:1], s46, v86
	s_nop 1
	v_addc_co_u32_e64 v17, s[0:1], 0, v87, s[0:1]
	s_nop 3
	global_store_dwordx4 v[16:17], v[8:11], off
	s_nop 1
	v_mfma_f32_16x16x32_bf16 v[8:11], v[12:15], v[4:7], 0
	v_mfma_f32_16x16x32_bf16 v[8:11], v[66:69], v[78:81], v[8:11]
	s_nop 7
	global_store_dwordx4 v[16:17], v[8:11], off offset:64
	s_nop 1
	v_mfma_f32_16x16x32_bf16 v[8:11], v[20:23], v[4:7], 0
	v_mfma_f32_16x16x32_bf16 v[4:7], v[70:73], v[4:7], 0
	v_mfma_f32_16x16x32_bf16 v[8:11], v[74:77], v[78:81], v[8:11]
	v_mfma_f32_16x16x32_bf16 v[0:3], v[0:3], v[78:81], v[4:7]
	s_nop 6
	global_store_dwordx4 v[16:17], v[8:11], off offset:128
	global_store_dwordx4 v[16:17], v[0:3], off offset:192
	s_waitcnt lgkmcnt(0)
	s_cbranch_scc0 .LBB0_341
	s_nop 0
	v_and_b32_e32 v0, 56, v27
	v_lshlrev_b32_e32 v1, 2, v248
	s_mov_b32 s38, 0x24000
	s_mov_b32 s37, 0xc000
	s_mov_b32 s36, 0x18000
	v_xor_b32_e32 v4, 4, v1
	v_xor_b32_e32 v5, 8, v1
	v_xor_b32_e32 v6, 16, v1
	v_xor_b32_e32 v7, 32, v1
	v_xor_b32_e32 v8, 64, v1
	v_xor_b32_e32 v9, 0x80, v1
	v_cmp_eq_u32_e32 vcc, 0, v248
	v_lshlrev_b32_e32 v32, 1, v0
	s_mov_b32 s12, s16
	s_branch .LBB0_344
